# tile-major KI layout (coalesced indexer K loads), hand-scheduled indexer loop, VALU-only top-k bisection counting, ds ops for LDS exchange
# speedup vs baseline: 1.0821x; 1.0821x over previous
; template <class Epi, bool BLKDIAG = false>
; __device__ __forceinline__ void gemm_phase(PG8_LAS unsigned char* lds, const Gemm g, const StaticOrder& S, const Epi& E) {
;     ...
;     PG8_WAIT_V(2); PG8_BAR;
;     PG8_STAGE(PG8_SB(1, 0), cB + kstep, voffB); PG8_STAGE(PG8_SA(1, 0), cA + kstep, voffA); PG8_STAGE(PG8_SB(1, 1), cB + hstepB + kstep, voffB);
;     PG8_WAIT_V(6); PG8_BAR;
;     __device__ __forceinline__ void operator()(const f32x4 (&acc)[2][2][4][2], const pg8::Unit& u, int wr, int wc, int fr, int fq) const {
;         const int pn = u.pn; const int row0 = u.pm * 256 + wr * 64 + fr, cl0 = wc * 32 + 8 * fq;
;         int kind = 0, ld = 0, coff = 0; bf16_t* dst = nullptr;
;         if (pn < 16) { dst = P.QL; ld = 4096; coff = pn * 256; }
;         else if (pn == 16) { kind = 3; }
;         else if (pn < 25) { dst = P.AG; ld = 2048; coff = (pn - 17) * 256; kind = 1; }
;         else if (pn < 29) { dst = P.QI; ld = 1024; coff = (pn - 25) * 256; }
;         else if (pn == 29) { kind = 4; }
;         else if (pn < 38) { dst = P.XR; ld = 2048; coff = (pn - 30) * 256; }
;         else if (pn < 46) { dst = P.RG; ld = 2048; coff = (pn - 38) * 256; kind = 1; }
;         else if (pn < 54) { dst = P.GA; ld = 2048; coff = (pn - 46) * 256; kind = 2; }
;         else { dst = P.GB; ld = 2048; coff = (pn - 54) * 256; kind = 2; }
; #pragma unroll
;         for (int ai = 0; ai < 2; ++ai)
; #pragma unroll
;             for (int m = 0; m < 4; ++m) { const size_t row = (size_t)(row0 + ai * 128 + m * 16);
; #pragma unroll
;                 for (int bj = 0; bj < 2; ++bj) { const int cl = cl0 + bj * 128; f32x4 v0 = acc[ai][bj][m][0], v1 = acc[ai][bj][m][1];
;                     if (kind <= 2) {
;                         if (kind == 1) {
; #pragma unroll
;                             for (int e = 0; e < 4; ++e) { v0[e] = v0[e] * fsigmoid(v0[e]); v1[e] = v1[e] * fsigmoid(v1[e]); }
;                         } else if (kind == 2) {
; #pragma unroll
;                             for (int e = 0; e < 4; ++e) { v0[e] = fsigmoid(v0[e]); v1[e] = fsigmoid(v1[e]); }
;                         }
;                         u32x4 w; w.x = cvt_pk_bf16(v0[0], v0[1]); w.y = cvt_pk_bf16(v0[2], v0[3]); w.z = cvt_pk_bf16(v1[0], v1[1]); w.w = cvt_pk_bf16(v1[2], v1[3]);
;                         *(u32x4*)(dst + row * ld + coff + cl) = w;
;                     } else if (kind == 3) {
.LBB0_130:
	s_mov_b64 s[82:83], 0x80
	s_and_b32 s1, s1, 3
	s_add_i32 m0, s74, 0x18000
	v_lshl_add_u64 v[4:5], v[4:5], 0, s[82:83]
	s_lshl_b32 s3, s0, 13
	s_lshl_b32 s5, s1, 12
	s_waitcnt vmcnt(2)
	s_barrier
	global_load_lds_dwordx4 v[4:5], off
	v_lshl_add_u64 v[2:3], v[2:3], 0, s[82:83]
	s_add_i32 m0, s74, 0x1a000
	s_add_i32 s81, s74, 0x8000
	s_add_i32 s62, s74, 0xa000
	global_load_lds_dwordx4 v[2:3], off
	v_lshl_add_u64 v[0:1], v[0:1], 0, s[82:83]
	s_mov_b32 m0, s81
	s_add_u32 s14, s12, 0x80080
	global_load_lds_dwordx4 v[0:1], off
	v_lshl_add_u64 v[0:1], v[6:7], 0, s[82:83]
	s_mov_b32 m0, s62
	s_addc_u32 s15, s13, 0
	global_load_lds_dwordx4 v[0:1], off
	s_add_i32 m0, s74, 0x1c000
	v_lshl_add_u64 v[0:1], s[14:15], 0, v[130:131]
	global_load_lds_dwordx4 v[0:1], off
	v_lshl_add_u64 v[0:1], s[14:15], 0, v[134:135]
	s_add_i32 m0, s74, 0x1e000
	v_and_b32_e32 v2, 32, v139
	global_load_lds_dwordx4 v[0:1], off
	v_and_b32_e32 v0, 15, v188
	v_lshlrev_b32_e32 v1, 1, v12
	v_lshl_or_b32 v170, s0, 6, v0
	v_lshl_or_b32 v0, v0, 6, v1
	v_bitop3_b32 v3, v0, s3, v2 bitop3:0xde
	v_lshlrev_b32_e32 v0, 6, v188
	s_movk_i32 s0, 0x3c0
	v_and_or_b32 v0, v0, s0, v1
	v_lshl_or_b32 v138, s1, 5, v12
	v_bitop3_b32 v171, s5, v0, v2 bitop3:0xf6
	v_and_b32_e32 v0, 15, v188
	v_mul_u32_u24_e32 v0, 0x70, v0
	v_lshlrev_b32_e32 v1, 5, v12
	v_sub_u32_e32 v0, v1, v0
	v_lshl_add_u32 v0, s1, 10, v0
	v_ashrrev_i32_e32 v1, 31, v0
	v_lshl_add_u64 v[142:143], s[50:51], 0, v[0:1]
	s_nop 0
	s_nop 0
	s_nop 0
	s_nop 0
	s_nop 0
	s_nop 0
	s_nop 0
	s_nop 0
	s_nop 0
	s_nop 0
	v_lshlrev_b32_e32 v0, 9, v188
	v_and_b32_e32 v0, 0x70000, v0
	v_lshlrev_b32_e32 v1, 12, v10
	v_or3_b32 v0, v8, v0, v1
	s_cmpk_lt_u32 s4, 0x100
	v_add_u32_e32 v148, v0, v9
	v_lshlrev_b32_e32 v0, 5, v11
	s_waitcnt vmcnt(6)
	s_cselect_b64 s[84:85], -1, 0
	s_cmp_gt_u32 s1, 1
	v_lshlrev_b32_e32 v136, 2, v138
	v_writelane_b32 v252, s78, 16
	v_and_b32_e32 v0, 0xf0000, v0
	s_cselect_b64 s[86:87], -1, 0
	s_movk_i32 s0, 0x50
	v_writelane_b32 v252, s79, 17
	v_lshl_add_u64 v[140:141], s[78:79], 0, v[136:137]
	v_lshl_add_u64 v[144:145], s[44:45], 0, v[136:137]
	v_or_b32_e32 v136, 0x200, v136
	v_or3_b32 v0, v8, v0, v1
	s_add_i32 s63, 0, 0x10000
	s_add_i32 s64, 0, 0x14000
	v_cmp_gt_u32_e64 s[0:1], s0, v138
	s_ashr_i32 s3, s34, 31
	s_ashr_i32 s33, s2, 31
	v_writelane_b32 v252, s44, 18
	v_mov_b32_e32 v149, v137
	v_add_u32_e32 v150, v0, v9
	v_lshl_add_u64 v[146:147], s[44:45], 0, v[136:137]
	v_mov_b32_e32 v151, v137
	v_mov_b64_e32 v[152:153], 0x1f00
	v_mov_b64_e32 v[154:155], 0x1eff
	v_add_u32_e32 v172, s63, v171
	v_add_u32_e32 v173, s64, v171
	v_add_u32_e32 v174, 0, v3
	s_barrier
	v_writelane_b32 v252, s45, 19
	s_branch .LBB0_133

; __device__ __forceinline__ void attn_item(const Ptrs& P, unsigned char* lds, int b, int tq0, int tid) {
;     const int lane = tid & 63, w = __builtin_amdgcn_readfirstlane(tid >> 6), g = lane >> 4, r16 = lane & 15;
;     constexpr int SP = 264;
;     bf16_t* stg = (bf16_t*)lds;
;     unsigned char* l2 = lds + 135168;
;     unsigned short* sel = (unsigned short*)l2;
;     unsigned* cntw = (unsigned*)(l2 + 2048);
;     unsigned* gte = (unsigned*)(l2 + 2048 + 256);
;     bf16_t* Pm = (bf16_t*)(l2 + 4096);
;     const size_t rowb = (size_t)b * T;
;     const int tmax = tq0 + 3;
;     if (tmax < 256 || (DBG & 4)) {
;         for (int i = tid; i < 1024; i += 512) sel[i] = (unsigned short)(((i & 255) <= tq0 + (i >> 8)) ? (i & 255) : 0);
;         __syncthreads();
;     } else {
;         bf16x8 Aq[4][2]; f32x4 wq[4];
; #pragma unroll
;         for (int q = 0; q < 4; ++q) { const bf16_t* qp = P.QI + (rowb + tq0 + q) * 1024 + r16 * 64 + 8 * g; Aq[q][0] = *(const bf16x8*)qp; Aq[q][1] = *(const bf16x8*)(qp + 32);
;             wq[q] = *(const f32x4*)(P.WI + (rowb + tq0 + q) * 16 + 4 * g); }
;         unsigned* KB = (unsigned*)lds;
;         const int nch = (tmax >> 6) + 1;
;         const int ni = (w < nch) ? ((nch - w + 7) >> 3) : 0;
;         bf16x8 Bk[4][2];
; __global__ void __launch_bounds__(512, 2) mega_fwd(Args args) {
;     ...
;         if (tid < 64) ((volatile unsigned*)(lds + 147456))[tid] = 0u;
;         __syncthreads();
.LBB0_460:
	v_cmp_gt_u32_e32 vcc, 64, v188
	s_and_saveexec_b64 s[0:1], vcc
	s_cbranch_execz .LBB0_462
	s_mov_b64 s[4:5], src_shared_base
	s_add_i32 s3, 0, 0x24000
	v_lshl_add_u32 v0, v188, 2, s3
	v_mov_b32_e32 v1, s5
	v_mov_b32_e32 v2, 0
	ds_write_b32 v0, v2
	s_waitcnt vmcnt(0) lgkmcnt(0)
.LBB0_462:
	s_or_b64 exec, exec, s[0:1]
	v_lshlrev_b32_e32 v2, 2, v188
	v_and_b32_e32 v4, 12, v2
	v_lshlrev_b32_e32 v2, 3, v188
	v_and_b32_e32 v194, 15, v188
	v_mov_b32_e32 v165, 0
	v_and_b32_e32 v196, 0xf8, v2
	v_lshlrev_b32_e32 v164, 7, v194
	v_lshlrev_b32_e32 v2, 1, v196
	v_mov_b32_e32 v3, v165
	v_lshl_add_u64 v[0:1], s[74:75], 0, v[164:165]
	v_and_b32_e32 v164, 48, v188
	v_lshl_add_u64 v[2:3], s[56:57], 0, v[2:3]
	s_mov_b64 s[12:13], 0x16000000
	v_lshlrev_b32_e32 v166, 3, v90
	v_lshl_add_u64 v[168:169], v[0:1], 0, v[164:165]
	v_bfe_u32 v1, v188, 2, 2
	v_lshl_add_u64 v[174:175], v[2:3], 0, s[12:13]
	v_lshrrev_b32_e32 v2, 5, v188
	v_or_b32_e32 v198, 30, v2
	v_lshl_add_u64 v[2:3], s[56:57], 0, v[164:165]
	s_mov_b64 s[12:13], 0x100000
	v_or_b32_e32 v1, v166, v1
	v_lshl_add_u64 v[176:177], v[2:3], 0, s[12:13]
	v_mul_u32_u24_e32 v1, 0x108, v1
	s_movk_i32 s12, 0x200
	v_add_lshl_u32 v205, v1, v4, 1
	v_sub_u32_e64 v1, s12, v188 clamp
	v_add_u32_e32 v1, 0x1ff, v1
	v_lshrrev_b32_e32 v178, 9, v1
	v_add_u32_e32 v1, 2, v178
	v_and_b32_e32 v207, 6, v1
	v_lshrrev_b32_e32 v1, 8, v188
	v_or_b32_e32 v208, 0x1ffc, v1
	v_lshl_add_u32 v1, v188, 1, 0
	v_add_u32_e32 v209, 0x21000, v1
	v_add_u32_e32 v1, 0x200, v188
	v_lshrrev_b32_e32 v1, 8, v1
	s_mov_b32 s22, 0
	s_lshr_b32 s3, s2, 1
	v_and_b32_e32 v179, 63, v188
	v_lshlrev_b32_e32 v0, 8, v194
	v_bfe_u32 v197, v188, 5, 1
	v_mul_u32_u24_e32 v5, 0xa0, v90
	v_add_u32_e32 v210, 0x1ffc, v1
	v_lshl_add_u32 v1, v198, 1, 0
	s_mov_b64 s[20:21], src_shared_base
	s_mov_b32 s23, 1
	v_cmp_eq_u32_e64 s[0:1], 0, v188
	v_lshl_add_u64 v[170:171], s[78:79], 0, v[164:165]
	v_lshlrev_b32_e32 v2, 4, v179
	v_mov_b32_e32 v3, 0
	v_lshl_add_u64 v[172:173], s[50:51], 0, v[2:3]
	v_cmp_eq_u32_e64 s[4:5], 0, v179
	v_cmp_gt_u32_e64 s[6:7], 16, v179
	v_cmp_lt_u32_e64 s[8:9], 31, v179
	v_cmp_eq_u32_e64 s[10:11], 48, v164
	v_and_b32_e32 v195, 0xff, v188
	v_mul_u32_u24_e32 v199, 0x50, v194
	v_mul_u32_u24_e32 v200, 0x210, v197
	v_mul_u32_u24_e32 v201, 0x210, v198
	v_mul_u32_u24_e32 v202, 0x210, v194
	v_lshl_add_u32 v203, v179, 2, 0
	v_lshl_or_b32 v204, v90, 10, v194
	v_mov_b32_e32 v167, v178
	v_add_u32_e32 v211, 0x21040, v1
	v_lshl_add_u32 v212, v194, 1, 0
	v_lshl_add_u32 v213, v197, 1, 0
	s_add_i32 s33, 0, 0x24100
	v_lshlrev_b32_e32 v180, 1, v0
	v_lshlrev_b32_e32 v214, 1, v5
	v_mov_b32_e32 v215, 0x80
	v_mov_b32_e32 v216, 0xf149f2ca
	s_mov_b32 s35, s3
	s_mov_b32 s80, s22
	s_waitcnt vmcnt(0) lgkmcnt(0)
	s_barrier
	s_branch .LBB0_464

; __global__ void __launch_bounds__(512, 2) mega_fwd(Args args) {
;     ...
;         for (int k = 0; k < NB; ++k) {
;             const int b = (hb + k) & 3;
;             for (;;) {
;                 __syncthreads();
;                 if (tid == 0) *(volatile int*)(lds + 147712) = (int)atomicAdd(ctl + 64 * b, 1u);
.LBB0_464:
	s_and_b32 s12, s35, 3
	v_lshl_or_b32 v217, s12, 13, v194
	s_add_i32 s12, s80, s3
	s_and_b32 s12, s12, 3
	s_lshl_b32 s13, s12, 8
	s_add_u32 s46, s56, s13
	s_addc_u32 s47, s57, 0
	s_lshl_b32 s81, s12, 13
	v_mov_b32_e32 v182, s81
	v_mov_b32_e32 v183, v165
	s_mov_b32 s82, s81
	s_mov_b64 s[48:49], 0
	s_branch .LBB0_466

; __device__ __forceinline__ unsigned f2key(float f) { const unsigned u = __builtin_bit_cast(unsigned, f); return (u & 0x80000000u) ? ~u : (u | 0x80000000u); }
; __device__ __forceinline__ void attn_item(const Ptrs& P, unsigned char* lds, int b, int tq0, int tid) {
;     ...
;         bf16x8 Aq[4][2]; f32x4 wq[4];
; #pragma unroll
;         for (int q = 0; q < 4; ++q) { const bf16_t* qp = P.QI + (rowb + tq0 + q) * 1024 + r16 * 64 + 8 * g; Aq[q][0] = *(const bf16x8*)qp; Aq[q][1] = *(const bf16x8*)(qp + 32);
;             wq[q] = *(const f32x4*)(P.WI + (rowb + tq0 + q) * 16 + 4 * g); }
;         unsigned* KB = (unsigned*)lds;
;         const int nch = (tmax >> 6) + 1;
;         const int ni = (w < nch) ? ((nch - w + 7) >> 3) : 0;
;         bf16x8 Bk[4][2];
;     ...
;         if (ni > 0) { TILE_LOAD(0, w, 0); TILE_LOAD(1, w, 1); }
; #pragma unroll 1
;         for (int it = 0; it < ni; ++it) {
;             const int c = 8 * it + w; const bool more = it + 1 < ni;
;             float pv[4][4], sv[4];
;             TILE_LOAD(2, c, 2); TILE_MATH(0, 0);
;             TILE_LOAD(3, c, 3); TILE_MATH(1, 1);
;             if (more) TILE_LOAD(0, c + 8, 0);
;             TILE_MATH(2, 2);
;             if (more) TILE_LOAD(1, c + 8, 1);
;             TILE_MATH(3, 3);
; #pragma unroll
;             for (int q = 0; q < 4; ++q) { float a0 = pv[q][0], b0 = pv[q][2], a1 = pv[q][1], b1 = pv[q][3];
;                 asm("s_nop 1\n\tv_permlane32_swap_b32 %0, %1" : "+v"(a0), "+v"(b0));
;                 asm("s_nop 1\n\tv_permlane32_swap_b32 %0, %1" : "+v"(a1), "+v"(b1));
;                 float x = a0 + b0, y = a1 + b1;
;                 asm("s_nop 1\n\tv_permlane16_swap_b32 %0, %1" : "+v"(x), "+v"(y));
;                 sv[q] = x + y; }
;             const int s = 64 * c + lane;
; #pragma unroll
;             for (int q = 0; q < 4; ++q) KB[q * 8192 + s] = (s <= tq0 + q) ? f2key(sv[q]) : 0u;
; __global__ void __launch_bounds__(512, 2) mega_fwd(Args args) {
;     ...
;                 if (tid == 0) *(volatile int*)(lds + 147712) = (int)atomicAdd(ctl + 64 * b, 1u);
;                 __syncthreads();
;                 const int item = *(volatile int*)(lds + 147712);
;                 if (item >= T / 4) break;
;                 attn_item(P, lds, b, 4 * ((T / 4 - 1) - item), tid);
.LBB0_469:
	s_or_b64 exec, exec, s[14:15]
	s_mov_b64 s[14:15], src_shared_base
	s_waitcnt vmcnt(0)
	v_readfirstlane_b32 s14, v1
	s_cmp_lg_u32 s33, -1
	s_cselect_b32 s15, s15, 0
	v_add_u32_e32 v2, s14, v0
	s_cselect_b32 s14, s33, 0
	v_mov_b32_e32 v0, s14
	v_mov_b32_e32 v1, s15
	ds_write_b32 v0, v2
	s_waitcnt vmcnt(0) lgkmcnt(0)
.LBB0_470:
	s_or_b64 exec, exec, s[12:13]
	s_cmp_lg_u32 s33, -1
	s_cselect_b32 s12, s33, 0
	s_cselect_b32 s13, s21, 0
	v_mov_b32_e32 v0, s12
	v_mov_b32_e32 v1, s13
	s_waitcnt lgkmcnt(0)
	s_barrier
	ds_read_b32 v0, v0
	s_waitcnt vmcnt(0) lgkmcnt(0)
	s_movk_i32 s12, 0x800
	s_waitcnt lgkmcnt(0)
	v_cmp_gt_i32_e32 vcc, s12, v0
	s_mov_b64 s[12:13], -1
	s_and_saveexec_b64 s[70:71], vcc
	s_cbranch_execz .LBB0_465
	v_lshlrev_b32_e32 v64, 2, v0
	v_sub_u32_e32 v124, 0x1ffc, v64
	v_readfirstlane_b32 s63, v188
	s_movk_i32 s12, 0xfc
	s_lshr_b32 s62, s63, 6
	v_cmp_lt_u32_e32 vcc, s12, v124
	s_and_saveexec_b64 s[12:13], vcc
	s_xor_b64 s[60:61], exec, s[12:13]
	s_cbranch_execz .LBB0_913
	v_sub_u32_e32 v126, 0x1fff, v64
	v_lshrrev_b32_e32 v125, 6, v126
	v_subrev_u32_e32 v0, s62, v125
	v_add_u32_e32 v65, 8, v0
	v_cmp_le_u32_e32 vcc, s62, v125
	v_cmp_lt_u32_e64 s[12:13], 7, v65
	s_and_b64 s[14:15], vcc, s[12:13]
	s_and_saveexec_b64 s[12:13], s[14:15]
	s_cbranch_execz .LBB0_479
	s_and_b32 s14, s63, 0xffffffc0
	v_add_u32_e32 v164, s81, v124
	s_ashr_i32 s15, s14, 31
	v_or_b32_e32 v40, 1, v164
	v_mov_b32_e32 v41, v165
	v_or_b32_e32 v32, 2, v164
	v_mov_b32_e32 v33, v165
	v_or_b32_e32 v34, 3, v164
	v_mov_b32_e32 v35, v165
	v_lshl_add_u64 v[48:49], s[14:15], 0, v[182:183]
	v_lshlrev_b64 v[0:1], 11, v[164:165]
	v_lshlrev_b64 v[8:9], 11, v[40:41]
	v_lshlrev_b64 v[16:17], 11, v[32:33]
	v_lshlrev_b64 v[24:25], 11, v[34:35]
	v_lshlrev_b64 v[34:35], 6, v[34:35]
	v_lshlrev_b64 v[32:33], 6, v[32:33]
	v_lshlrev_b64 v[40:41], 6, v[40:41]
	v_lshlrev_b64 v[42:43], 6, v[164:165]
	v_lshlrev_b64 v[48:49], 7, v[48:49]
	v_lshl_add_u64 v[4:5], v[168:169], 0, v[0:1]
	v_lshl_add_u64 v[12:13], v[168:169], 0, v[8:9]
	v_lshl_add_u64 v[20:21], v[168:169], 0, v[16:17]
	v_lshl_add_u64 v[28:29], v[168:169], 0, v[24:25]
	v_lshl_add_u64 v[34:35], v[170:171], 0, v[34:35]
	v_lshl_add_u64 v[36:37], v[170:171], 0, v[32:33]
	v_lshl_add_u64 v[40:41], v[170:171], 0, v[40:41]
	v_lshl_add_u64 v[44:45], v[170:171], 0, v[42:43]
	v_lshl_add_u64 v[60:61], v[172:173], 0, v[48:49]
	global_load_dwordx4 v[0:3], v[4:5], off
	s_nop 0
	global_load_dwordx4 v[4:7], v[4:5], off offset:64
	s_nop 0
	global_load_dwordx4 v[8:11], v[12:13], off
	s_nop 0
	global_load_dwordx4 v[12:15], v[12:13], off offset:64
	s_nop 0
	global_load_dwordx4 v[16:19], v[20:21], off
	s_nop 0
	global_load_dwordx4 v[20:23], v[20:21], off offset:64
	s_nop 0
	global_load_dwordx4 v[24:27], v[28:29], off
	s_nop 0
	global_load_dwordx4 v[28:31], v[28:29], off offset:64
	s_nop 0
	global_load_dwordx4 v[32:35], v[34:35], off
	s_nop 0
	global_load_dwordx4 v[36:39], v[36:37], off
	s_nop 0
	global_load_dwordx4 v[40:43], v[40:41], off
	s_nop 0
	global_load_dwordx4 v[44:47], v[44:45], off
	s_nop 0
	v_lshrrev_b32_e32 v127, 3, v65
	v_sub_u32_e32 v128, 0x1ffd, v64
	v_sub_u32_e32 v129, 0x1ffe, v64
	v_mov_b64_e32 v[150:151], v[60:61]
	s_mov_b64 s[18:19], 0x1000
	v_lshl_add_u64 v[152:153], v[60:61], 0, s[18:19]
	global_load_dwordx4 v[48:51], v[150:151], off
	global_load_dwordx4 v[52:55], v[150:151], off offset:1024
	global_load_dwordx4 v[56:59], v[150:151], off offset:2048
	global_load_dwordx4 v[60:63], v[150:151], off offset:3072
	global_load_dwordx4 v[64:67], v[152:153], off
	global_load_dwordx4 v[68:71], v[152:153], off offset:1024
	global_load_dwordx4 v[72:75], v[152:153], off offset:2048
	global_load_dwordx4 v[76:79], v[152:153], off offset:3072
	s_mov_b64 s[18:19], 0x10000
	v_lshl_add_u64 v[150:151], v[150:151], 0, s[18:19]
	v_lshl_add_u64 v[152:153], v[152:153], 0, s[18:19]
	s_mov_b32 s20, 0
	v_lshl_add_u32 v130, s62, 8, v203
	v_add_u32_e32 v155, 0x10000, v130
	v_add_u32_e32 v154, s14, v179
	s_nop 0
	v_readfirstlane_b32 s14, v127
.Lidx_loop:
	s_waitcnt vmcnt(6)
	v_mfma_f32_16x16x32_bf16 v[80:83], v[0:3], v[48:51], 0
	v_mfma_f32_16x16x32_bf16 v[84:87], v[8:11], v[48:51], 0
	v_mfma_f32_16x16x32_bf16 v[88:91], v[16:19], v[48:51], 0
	v_mfma_f32_16x16x32_bf16 v[92:95], v[24:27], v[48:51], 0
	v_mfma_f32_16x16x32_bf16 v[80:83], v[4:7], v[52:55], v[80:83]
	v_mfma_f32_16x16x32_bf16 v[84:87], v[12:15], v[52:55], v[84:87]
	v_mfma_f32_16x16x32_bf16 v[88:91], v[20:23], v[52:55], v[88:91]
	v_mfma_f32_16x16x32_bf16 v[92:95], v[28:31], v[52:55], v[92:95]
	global_load_dwordx4 v[48:51], v[150:151], off
	global_load_dwordx4 v[52:55], v[150:151], off offset:1024
	s_waitcnt vmcnt(6)
	v_mfma_f32_16x16x32_bf16 v[96:99], v[0:3], v[56:59], 0
	v_mfma_f32_16x16x32_bf16 v[100:103], v[8:11], v[56:59], 0
	v_mfma_f32_16x16x32_bf16 v[104:107], v[16:19], v[56:59], 0
	v_mfma_f32_16x16x32_bf16 v[108:111], v[24:27], v[56:59], 0
	v_mfma_f32_16x16x32_bf16 v[96:99], v[4:7], v[60:63], v[96:99]
	v_mfma_f32_16x16x32_bf16 v[100:103], v[12:15], v[60:63], v[100:103]
	v_mfma_f32_16x16x32_bf16 v[104:107], v[20:23], v[60:63], v[104:107]
	v_mfma_f32_16x16x32_bf16 v[108:111], v[28:31], v[60:63], v[108:111]
	global_load_dwordx4 v[56:59], v[150:151], off offset:2048
	global_load_dwordx4 v[60:63], v[150:151], off offset:3072
	v_max_f32_e32 v80, 0, v80
	v_max_f32_e32 v84, 0, v84
	v_max_f32_e32 v88, 0, v88
	v_max_f32_e32 v92, 0, v92
	v_max_f32_e32 v81, 0, v81
	v_max_f32_e32 v85, 0, v85
	v_max_f32_e32 v89, 0, v89
	v_max_f32_e32 v93, 0, v93
	v_max_f32_e32 v82, 0, v82
	v_max_f32_e32 v86, 0, v86
	v_max_f32_e32 v90, 0, v90
	v_max_f32_e32 v94, 0, v94
	v_max_f32_e32 v83, 0, v83
	v_max_f32_e32 v87, 0, v87
	v_max_f32_e32 v91, 0, v91
	v_max_f32_e32 v95, 0, v95
	v_mul_f32_e32 v132, v44, v80
	v_mul_f32_e32 v136, v40, v84
	v_mul_f32_e32 v140, v36, v88
	v_mul_f32_e32 v144, v32, v92
	v_fmac_f32_e32 v132, v45, v81
	v_fmac_f32_e32 v136, v41, v85
	v_fmac_f32_e32 v140, v37, v89
	v_fmac_f32_e32 v144, v33, v93
	v_fmac_f32_e32 v132, v46, v82
	v_fmac_f32_e32 v136, v42, v86
	v_fmac_f32_e32 v140, v38, v90
	v_fmac_f32_e32 v144, v34, v94
	v_fmac_f32_e32 v132, v47, v83
	v_fmac_f32_e32 v136, v43, v87
	v_fmac_f32_e32 v140, v39, v91
	v_fmac_f32_e32 v144, v35, v95
	s_waitcnt vmcnt(6)
; __device__ __forceinline__ unsigned f2key(float f) { const unsigned u = __builtin_bit_cast(unsigned, f); return (u & 0x80000000u) ? ~u : (u | 0x80000000u); }
; #define TILE_LOAD(SLOT, CC, TT) do { const bf16_t* kp = P.KI + (rowb + 64 * (CC) + 16 * (TT) + r16) * 64 + 8 * g; Bk[SLOT][0] = *(const bf16x8*)kp; Bk[SLOT][1] = *(const bf16x8*)(kp + 32); } while (0)
; #define TILE_MATH(SLOT, TT) do { _Pragma("unroll") for (int q = 0; q < 4; ++q) { f32x4 a = {0.f, 0.f, 0.f, 0.f}; \
;             a = mfma16(Aq[q][0], Bk[SLOT][0], a); a = mfma16(Aq[q][1], Bk[SLOT][1], a); \
;             pv[q][TT] = wq[q][0] * fmaxf(a[0], 0.f) + wq[q][1] * fmaxf(a[1], 0.f) + wq[q][2] * fmaxf(a[2], 0.f) + wq[q][3] * fmaxf(a[3], 0.f); } } while (0)
; __device__ __forceinline__ void attn_item(const Ptrs& P, unsigned char* lds, int b, int tq0, int tid) {
;     ...
;             TILE_LOAD(2, c, 2); TILE_MATH(0, 0);
;             TILE_LOAD(3, c, 3); TILE_MATH(1, 1);
;             if (more) TILE_LOAD(0, c + 8, 0);
;             TILE_MATH(2, 2);
;             if (more) TILE_LOAD(1, c + 8, 1);
;             TILE_MATH(3, 3);
; #pragma unroll
;             for (int q = 0; q < 4; ++q) { float a0 = pv[q][0], b0 = pv[q][2], a1 = pv[q][1], b1 = pv[q][3];
;                 asm("s_nop 1\n\tv_permlane32_swap_b32 %0, %1" : "+v"(a0), "+v"(b0));
;                 asm("s_nop 1\n\tv_permlane32_swap_b32 %0, %1" : "+v"(a1), "+v"(b1));
;                 float x = a0 + b0, y = a1 + b1;
;                 asm("s_nop 1\n\tv_permlane16_swap_b32 %0, %1" : "+v"(x), "+v"(y));
;                 sv[q] = x + y; }
;             const int s = 64 * c + lane;
; #pragma unroll
;             for (int q = 0; q < 4; ++q) KB[q * 8192 + s] = (s <= tq0 + q) ? f2key(sv[q]) : 0u;
;         }
	v_mfma_f32_16x16x32_bf16 v[80:83], v[0:3], v[64:67], 0
	v_mfma_f32_16x16x32_bf16 v[84:87], v[8:11], v[64:67], 0
	v_mfma_f32_16x16x32_bf16 v[88:91], v[16:19], v[64:67], 0
	v_mfma_f32_16x16x32_bf16 v[92:95], v[24:27], v[64:67], 0
	v_mfma_f32_16x16x32_bf16 v[80:83], v[4:7], v[68:71], v[80:83]
	v_mfma_f32_16x16x32_bf16 v[84:87], v[12:15], v[68:71], v[84:87]
	v_mfma_f32_16x16x32_bf16 v[88:91], v[20:23], v[68:71], v[88:91]
	v_mfma_f32_16x16x32_bf16 v[92:95], v[28:31], v[68:71], v[92:95]
	global_load_dwordx4 v[64:67], v[152:153], off
	global_load_dwordx4 v[68:71], v[152:153], off offset:1024
	v_max_f32_e32 v96, 0, v96
	v_max_f32_e32 v100, 0, v100
	v_max_f32_e32 v104, 0, v104
	v_max_f32_e32 v108, 0, v108
	v_max_f32_e32 v97, 0, v97
	v_max_f32_e32 v101, 0, v101
	v_max_f32_e32 v105, 0, v105
	v_max_f32_e32 v109, 0, v109
	v_max_f32_e32 v98, 0, v98
	v_max_f32_e32 v102, 0, v102
	v_max_f32_e32 v106, 0, v106
	v_max_f32_e32 v110, 0, v110
	v_max_f32_e32 v99, 0, v99
	v_max_f32_e32 v103, 0, v103
	v_max_f32_e32 v107, 0, v107
	v_max_f32_e32 v111, 0, v111
	v_mul_f32_e32 v133, v44, v96
	v_mul_f32_e32 v137, v40, v100
	v_mul_f32_e32 v141, v36, v104
	v_mul_f32_e32 v145, v32, v108
	v_fmac_f32_e32 v133, v45, v97
	v_fmac_f32_e32 v137, v41, v101
	v_fmac_f32_e32 v141, v37, v105
	v_fmac_f32_e32 v145, v33, v109
	v_fmac_f32_e32 v133, v46, v98
	v_fmac_f32_e32 v137, v42, v102
	v_fmac_f32_e32 v141, v38, v106
	v_fmac_f32_e32 v145, v34, v110
	v_fmac_f32_e32 v133, v47, v99
	v_fmac_f32_e32 v137, v43, v103
	v_fmac_f32_e32 v141, v39, v107
	v_fmac_f32_e32 v145, v35, v111
	s_waitcnt vmcnt(6)
	v_mfma_f32_16x16x32_bf16 v[96:99], v[0:3], v[72:75], 0
	v_mfma_f32_16x16x32_bf16 v[100:103], v[8:11], v[72:75], 0
	v_mfma_f32_16x16x32_bf16 v[104:107], v[16:19], v[72:75], 0
	v_mfma_f32_16x16x32_bf16 v[108:111], v[24:27], v[72:75], 0
	v_mfma_f32_16x16x32_bf16 v[96:99], v[4:7], v[76:79], v[96:99]
	v_mfma_f32_16x16x32_bf16 v[100:103], v[12:15], v[76:79], v[100:103]
	v_mfma_f32_16x16x32_bf16 v[104:107], v[20:23], v[76:79], v[104:107]
	v_mfma_f32_16x16x32_bf16 v[108:111], v[28:31], v[76:79], v[108:111]
	global_load_dwordx4 v[72:75], v[152:153], off offset:2048
	global_load_dwordx4 v[76:79], v[152:153], off offset:3072
	v_lshl_add_u64 v[150:151], v[150:151], 0, s[18:19]
	v_lshl_add_u64 v[152:153], v[152:153], 0, s[18:19]
	v_max_f32_e32 v80, 0, v80
	v_max_f32_e32 v84, 0, v84
	v_max_f32_e32 v88, 0, v88
	v_max_f32_e32 v92, 0, v92
	v_max_f32_e32 v81, 0, v81
	v_max_f32_e32 v85, 0, v85
	v_max_f32_e32 v89, 0, v89
	v_max_f32_e32 v93, 0, v93
	v_max_f32_e32 v82, 0, v82
	v_max_f32_e32 v86, 0, v86
	v_max_f32_e32 v90, 0, v90
	v_max_f32_e32 v94, 0, v94
	v_max_f32_e32 v83, 0, v83
	v_max_f32_e32 v87, 0, v87
	v_max_f32_e32 v91, 0, v91
	v_max_f32_e32 v95, 0, v95
	v_mul_f32_e32 v134, v44, v80
	v_mul_f32_e32 v138, v40, v84
	v_mul_f32_e32 v142, v36, v88
	v_mul_f32_e32 v146, v32, v92
	v_fmac_f32_e32 v134, v45, v81
	v_fmac_f32_e32 v138, v41, v85
	v_fmac_f32_e32 v142, v37, v89
	v_fmac_f32_e32 v146, v33, v93
	v_fmac_f32_e32 v134, v46, v82
	v_fmac_f32_e32 v138, v42, v86
	v_fmac_f32_e32 v142, v38, v90
	v_fmac_f32_e32 v146, v34, v94
	v_fmac_f32_e32 v134, v47, v83
	v_fmac_f32_e32 v138, v43, v87
	v_fmac_f32_e32 v142, v39, v91
	v_fmac_f32_e32 v146, v35, v95
	v_max_f32_e32 v96, 0, v96
	v_max_f32_e32 v100, 0, v100
	v_max_f32_e32 v104, 0, v104
	v_max_f32_e32 v108, 0, v108
	v_max_f32_e32 v97, 0, v97
	v_max_f32_e32 v101, 0, v101
	v_max_f32_e32 v105, 0, v105
	v_max_f32_e32 v109, 0, v109
	v_max_f32_e32 v98, 0, v98
	v_max_f32_e32 v102, 0, v102
	v_max_f32_e32 v106, 0, v106
	v_max_f32_e32 v110, 0, v110
	v_max_f32_e32 v99, 0, v99
	v_max_f32_e32 v103, 0, v103
	v_max_f32_e32 v107, 0, v107
	v_max_f32_e32 v111, 0, v111
	v_mul_f32_e32 v135, v44, v96
	v_mul_f32_e32 v139, v40, v100
	v_mul_f32_e32 v143, v36, v104
	v_mul_f32_e32 v147, v32, v108
	v_fmac_f32_e32 v135, v45, v97
	v_fmac_f32_e32 v139, v41, v101
	v_fmac_f32_e32 v143, v37, v105
	v_fmac_f32_e32 v147, v33, v109
	v_fmac_f32_e32 v135, v46, v98
	v_fmac_f32_e32 v139, v42, v102
	v_fmac_f32_e32 v143, v38, v106
	v_fmac_f32_e32 v147, v34, v110
	v_fmac_f32_e32 v135, v47, v99
	v_fmac_f32_e32 v139, v43, v103
	v_fmac_f32_e32 v143, v39, v107
	v_fmac_f32_e32 v147, v35, v111
	s_nop 1
	v_permlane32_swap_b32_e32 v132, v134
	v_permlane32_swap_b32_e32 v133, v135
	v_permlane32_swap_b32_e32 v136, v138
	v_permlane32_swap_b32_e32 v137, v139
	v_permlane32_swap_b32_e32 v140, v142
	v_permlane32_swap_b32_e32 v141, v143
	v_permlane32_swap_b32_e32 v144, v146
	v_permlane32_swap_b32_e32 v145, v147
	v_add_f32_e32 v112, v132, v134
	v_add_f32_e32 v113, v133, v135
	v_add_f32_e32 v114, v136, v138
	v_add_f32_e32 v115, v137, v139
	v_add_f32_e32 v116, v140, v142
	v_add_f32_e32 v117, v141, v143
	v_add_f32_e32 v118, v144, v146
	v_add_f32_e32 v119, v145, v147
	s_nop 1
	v_permlane16_swap_b32_e32 v112, v113
	v_permlane16_swap_b32_e32 v114, v115
	v_permlane16_swap_b32_e32 v116, v117
	v_permlane16_swap_b32_e32 v118, v119
	v_add_u32_e32 v156, 0x800, v130
	v_add_u32_e32 v157, 0x800, v155
	v_add_f32_e32 v120, v112, v113
	v_add_f32_e32 v121, v114, v115
	v_add_f32_e32 v122, v116, v117
	v_add_f32_e32 v123, v118, v119
	v_ashrrev_i32_e32 v112, 31, v120
	v_ashrrev_i32_e32 v113, 31, v121
	v_ashrrev_i32_e32 v114, 31, v122
	v_ashrrev_i32_e32 v115, 31, v123
	v_cmp_le_u32_e32 vcc, v154, v124
	v_cmp_le_u32_e64 s[16:17], v154, v128
	v_cmp_le_u32_e64 s[44:45], v154, v129
	v_cmp_le_u32_e64 s[78:79], v154, v126
	v_or_b32_e32 v112, 0x80000000, v112
	v_or_b32_e32 v113, 0x80000000, v113
	v_or_b32_e32 v114, 0x80000000, v114
	v_or_b32_e32 v115, 0x80000000, v115
	v_xor_b32_e32 v120, v120, v112
	v_xor_b32_e32 v121, v121, v113
	v_xor_b32_e32 v122, v122, v114
	v_xor_b32_e32 v123, v123, v115
	v_cndmask_b32_e32 v120, 0, v120, vcc
	v_cndmask_b32_e64 v121, 0, v121, s[16:17]
	v_cndmask_b32_e64 v122, 0, v122, s[44:45]
	v_cndmask_b32_e64 v123, 0, v123, s[78:79]
	ds_write2st64_b32 v130, v120, v121 offset1:128
	ds_write2st64_b32 v155, v122, v123 offset1:128
	v_mov_b32_e32 v130, v156
	v_mov_b32_e32 v155, v157
	v_add_u32_e32 v154, 0x200, v154
	s_add_i32 s20, s20, 1
	s_cmp_lt_u32 s20, s14
	s_cbranch_scc1 .Lidx_loop
	s_waitcnt vmcnt(0)
	s_branch .LBB0_479
	s_nop 0
	s_nop 0
	s_nop 0
	s_nop 0
	s_nop 0
	s_nop 0
	s_nop 0

; __device__ __forceinline__ void attn_item(const Ptrs& P, unsigned char* lds, int b, int tq0, int tid) {
;     ...
;         volatile unsigned* xw = (volatile unsigned*)(lds + 147456);
;         const unsigned seq = (xw[32 + w] + 1u) & 0xffu; if (lane == 0) xw[32 + w] = seq;
.LBB0_487:
	s_or_b64 exec, exec, s[12:13]
	s_lshl_b32 s83, s62, 2
	s_add_i32 s12, s83, 0
	s_add_i32 s20, s12, 0x24080
	v_mov_b64_e32 v[64:65], s[20:21]
	s_waitcnt lgkmcnt(0)
	s_barrier
	ds_read_b32 v64, v64
	s_waitcnt vmcnt(0) lgkmcnt(0)
	v_add_u32_e32 v64, 1, v64
	v_and_b32_e32 v96, 0xff, v64
	s_and_saveexec_b64 s[12:13], s[4:5]
	s_cbranch_execz .LBB0_489
	v_mov_b64_e32 v[64:65], s[20:21]
	ds_write_b32 v64, v96
	s_waitcnt vmcnt(0) lgkmcnt(0)

; #define PAIR_XCHG(SLOT, TAG, MINE, OTHER) do { const unsigned tg_ = (seq << 8) | (unsigned)(TAG); if (lane == 0) xw[w * 4 + (SLOT)] = ((MINE) << 16) | tg_; \
;             unsigned v_; do { v_ = xw[(w ^ 1) * 4 + (SLOT)]; } while ((v_ & 0xffffu) != tg_); OTHER = v_ >> 16; } while (0)
; __device__ __forceinline__ void attn_item(const Ptrs& P, unsigned char* lds, int b, int tq0, int tid) {
;     ...
;         unsigned th = 0u;
;     ...
;             const unsigned cand = th | (1u << bit); unsigned cnt = 0, oth;
; #pragma unroll
;             for (int k = 0; k < 4; ++k) if (16 * k < nact) {
; #pragma unroll
;                 for (int r = 16 * k; r < 16 * k + 16; ++r) cnt += (unsigned)__popcll(__ballot(k2[r] >= cand)); }
;             PAIR_XCHG(bit & 1, 1 + bit, cnt, oth);
;             cnt += oth;
;             if (cnt >= 256u) th = cand;
;             if (cnt == 256u) break;
.LBB0_490:
	v_lshl_or_b32 v24, 1, s75, v5
	v_mov_b32_e32 v25, 0
	s_cmp_eq_u64 s[18:19], 0
	s_cbranch_scc1 .Lbis_cnt_done
	v_cmp_ge_u32_e64 s[78:79], v6, v24
	v_cmp_ge_u32_e64 s[84:85], v95, v24
	v_cmp_ge_u32_e64 s[86:87], v94, v24
	v_addc_co_u32_e64 v25, s[88:89], 0, v25, s[78:79]
	v_cmp_ge_u32_e64 s[78:79], v93, v24
	v_addc_co_u32_e64 v25, s[88:89], 0, v25, s[84:85]
	v_cmp_ge_u32_e64 s[84:85], v92, v24
	v_addc_co_u32_e64 v25, s[88:89], 0, v25, s[86:87]
	v_cmp_ge_u32_e64 s[86:87], v91, v24
	v_addc_co_u32_e64 v25, s[88:89], 0, v25, s[78:79]
	v_cmp_ge_u32_e64 s[78:79], v90, v24
	v_addc_co_u32_e64 v25, s[88:89], 0, v25, s[84:85]
	v_cmp_ge_u32_e64 s[84:85], v89, v24
	v_addc_co_u32_e64 v25, s[88:89], 0, v25, s[86:87]
	v_cmp_ge_u32_e64 s[86:87], v88, v24
	v_addc_co_u32_e64 v25, s[88:89], 0, v25, s[78:79]
	v_cmp_ge_u32_e64 s[78:79], v87, v24
	v_addc_co_u32_e64 v25, s[88:89], 0, v25, s[84:85]
	v_cmp_ge_u32_e64 s[84:85], v86, v24
	v_addc_co_u32_e64 v25, s[88:89], 0, v25, s[86:87]
	v_cmp_ge_u32_e64 s[86:87], v85, v24
	v_addc_co_u32_e64 v25, s[88:89], 0, v25, s[78:79]
	v_cmp_ge_u32_e64 s[78:79], v84, v24
	v_addc_co_u32_e64 v25, s[88:89], 0, v25, s[84:85]
	v_cmp_ge_u32_e64 s[84:85], v83, v24
	v_addc_co_u32_e64 v25, s[88:89], 0, v25, s[86:87]
	v_cmp_ge_u32_e64 s[86:87], v82, v24
	v_addc_co_u32_e64 v25, s[88:89], 0, v25, s[78:79]
	v_cmp_ge_u32_e64 s[78:79], v81, v24
	v_addc_co_u32_e64 v25, s[88:89], 0, v25, s[84:85]
	v_addc_co_u32_e64 v25, s[88:89], 0, v25, s[86:87]
	v_addc_co_u32_e64 v25, s[88:89], 0, v25, s[78:79]
	s_cmp_eq_u64 s[16:17], 0
	s_cbranch_scc1 .Lbis_cnt_done
	v_cmp_ge_u32_e64 s[78:79], v4, v24
	v_cmp_ge_u32_e64 s[84:85], v80, v24
	v_cmp_ge_u32_e64 s[86:87], v79, v24
	v_addc_co_u32_e64 v25, s[88:89], 0, v25, s[78:79]
	v_cmp_ge_u32_e64 s[78:79], v78, v24
	v_addc_co_u32_e64 v25, s[88:89], 0, v25, s[84:85]
	v_cmp_ge_u32_e64 s[84:85], v77, v24
	v_addc_co_u32_e64 v25, s[88:89], 0, v25, s[86:87]
	v_cmp_ge_u32_e64 s[86:87], v76, v24
	v_addc_co_u32_e64 v25, s[88:89], 0, v25, s[78:79]
	v_cmp_ge_u32_e64 s[78:79], v75, v24
	v_addc_co_u32_e64 v25, s[88:89], 0, v25, s[84:85]
	v_cmp_ge_u32_e64 s[84:85], v74, v24
	v_addc_co_u32_e64 v25, s[88:89], 0, v25, s[86:87]
	v_cmp_ge_u32_e64 s[86:87], v73, v24
	v_addc_co_u32_e64 v25, s[88:89], 0, v25, s[78:79]
	v_cmp_ge_u32_e64 s[78:79], v72, v24
	v_addc_co_u32_e64 v25, s[88:89], 0, v25, s[84:85]
	v_cmp_ge_u32_e64 s[84:85], v71, v24
	v_addc_co_u32_e64 v25, s[88:89], 0, v25, s[86:87]
	v_cmp_ge_u32_e64 s[86:87], v70, v24
	v_addc_co_u32_e64 v25, s[88:89], 0, v25, s[78:79]
	v_cmp_ge_u32_e64 s[78:79], v69, v24
	v_addc_co_u32_e64 v25, s[88:89], 0, v25, s[84:85]
	v_cmp_ge_u32_e64 s[84:85], v68, v24
	v_addc_co_u32_e64 v25, s[88:89], 0, v25, s[86:87]
	v_cmp_ge_u32_e64 s[86:87], v67, v24
	v_addc_co_u32_e64 v25, s[88:89], 0, v25, s[78:79]
	v_cmp_ge_u32_e64 s[78:79], v66, v24
	v_addc_co_u32_e64 v25, s[88:89], 0, v25, s[84:85]
	v_addc_co_u32_e64 v25, s[88:89], 0, v25, s[86:87]
	v_addc_co_u32_e64 v25, s[88:89], 0, v25, s[78:79]
	s_cmp_eq_u64 s[14:15], 0
	s_cbranch_scc1 .Lbis_cnt_done
	v_cmp_ge_u32_e64 s[78:79], v2, v24
	v_cmp_ge_u32_e64 s[84:85], v65, v24
	v_cmp_ge_u32_e64 s[86:87], v64, v24
	v_addc_co_u32_e64 v25, s[88:89], 0, v25, s[78:79]
	v_cmp_ge_u32_e64 s[78:79], v49, v24
	v_addc_co_u32_e64 v25, s[88:89], 0, v25, s[84:85]
	v_cmp_ge_u32_e64 s[84:85], v48, v24
	v_addc_co_u32_e64 v25, s[88:89], 0, v25, s[86:87]
	v_cmp_ge_u32_e64 s[86:87], v46, v24
	v_addc_co_u32_e64 v25, s[88:89], 0, v25, s[78:79]
	v_cmp_ge_u32_e64 s[78:79], v35, v24
	v_addc_co_u32_e64 v25, s[88:89], 0, v25, s[84:85]
	v_cmp_ge_u32_e64 s[84:85], v34, v24
	v_addc_co_u32_e64 v25, s[88:89], 0, v25, s[86:87]
	v_cmp_ge_u32_e64 s[86:87], v33, v24
	v_addc_co_u32_e64 v25, s[88:89], 0, v25, s[78:79]
	v_cmp_ge_u32_e64 s[78:79], v32, v24
	v_addc_co_u32_e64 v25, s[88:89], 0, v25, s[84:85]
	v_cmp_ge_u32_e64 s[84:85], v31, v24
	v_addc_co_u32_e64 v25, s[88:89], 0, v25, s[86:87]
	v_cmp_ge_u32_e64 s[86:87], v30, v24
	v_addc_co_u32_e64 v25, s[88:89], 0, v25, s[78:79]
	v_cmp_ge_u32_e64 s[78:79], v28, v24
	v_addc_co_u32_e64 v25, s[88:89], 0, v25, s[84:85]
	v_cmp_ge_u32_e64 s[84:85], v23, v24
	v_addc_co_u32_e64 v25, s[88:89], 0, v25, s[86:87]
	v_cmp_ge_u32_e64 s[86:87], v22, v24
	v_addc_co_u32_e64 v25, s[88:89], 0, v25, s[78:79]
	v_cmp_ge_u32_e64 s[78:79], v21, v24
	v_addc_co_u32_e64 v25, s[88:89], 0, v25, s[84:85]
	v_addc_co_u32_e64 v25, s[88:89], 0, v25, s[86:87]
	v_addc_co_u32_e64 v25, s[88:89], 0, v25, s[78:79]
	s_cmp_eq_u64 vcc, 0
	s_cbranch_scc1 .Lbis_cnt_done
	v_cmp_ge_u32_e64 s[78:79], v0, v24
	v_cmp_ge_u32_e64 s[84:85], v20, v24
	v_cmp_ge_u32_e64 s[86:87], v19, v24
	v_addc_co_u32_e64 v25, s[88:89], 0, v25, s[78:79]
	v_cmp_ge_u32_e64 s[78:79], v18, v24
	v_addc_co_u32_e64 v25, s[88:89], 0, v25, s[84:85]
	v_cmp_ge_u32_e64 s[84:85], v17, v24
	v_addc_co_u32_e64 v25, s[88:89], 0, v25, s[86:87]
	v_cmp_ge_u32_e64 s[86:87], v16, v24
	v_addc_co_u32_e64 v25, s[88:89], 0, v25, s[78:79]
	v_cmp_ge_u32_e64 s[78:79], v15, v24
	v_addc_co_u32_e64 v25, s[88:89], 0, v25, s[84:85]
	v_cmp_ge_u32_e64 s[84:85], v14, v24
	v_addc_co_u32_e64 v25, s[88:89], 0, v25, s[86:87]
	v_cmp_ge_u32_e64 s[86:87], v13, v24
	v_addc_co_u32_e64 v25, s[88:89], 0, v25, s[78:79]
	v_cmp_ge_u32_e64 s[78:79], v12, v24
	v_addc_co_u32_e64 v25, s[88:89], 0, v25, s[84:85]
	v_cmp_ge_u32_e64 s[84:85], v11, v24
	v_addc_co_u32_e64 v25, s[88:89], 0, v25, s[86:87]
	v_cmp_ge_u32_e64 s[86:87], v10, v24
	v_addc_co_u32_e64 v25, s[88:89], 0, v25, s[78:79]
	v_cmp_ge_u32_e64 s[78:79], v9, v24
	v_addc_co_u32_e64 v25, s[88:89], 0, v25, s[84:85]
	v_cmp_ge_u32_e64 s[84:85], v8, v24
	v_addc_co_u32_e64 v25, s[88:89], 0, v25, s[86:87]
	v_cmp_ge_u32_e64 s[86:87], v7, v24
	v_addc_co_u32_e64 v25, s[88:89], 0, v25, s[78:79]
	v_cmp_ge_u32_e64 s[78:79], v3, v24
	v_addc_co_u32_e64 v25, s[88:89], 0, v25, s[84:85]
	v_addc_co_u32_e64 v25, s[88:89], 0, v25, s[86:87]
	v_addc_co_u32_e64 v25, s[88:89], 0, v25, s[78:79]
.Lbis_cnt_done:
	s_nop 1
	v_add_u32_dpp v25, v25, v25 row_ror:1 row_mask:0xf bank_mask:0xf
	s_nop 1
	v_add_u32_dpp v25, v25, v25 row_ror:2 row_mask:0xf bank_mask:0xf
	s_nop 1
	v_add_u32_dpp v25, v25, v25 row_ror:4 row_mask:0xf bank_mask:0xf
	s_nop 1
	v_add_u32_dpp v25, v25, v25 row_ror:8 row_mask:0xf bank_mask:0xf
	s_nop 1
	v_readlane_b32 s78, v25, 0
	v_readlane_b32 s79, v25, 16
	v_readlane_b32 s84, v25, 32
	v_readlane_b32 s85, v25, 48
	s_nop 3
	s_add_i32 s78, s78, s79
	s_add_i32 s84, s84, s85
	s_add_i32 s78, s78, s84
	v_mov_b32_e32 v25, s78
.LBB0_498:
	s_add_i32 s12, s75, 1
	v_or_b32_e32 v26, s12, v1
	s_and_b32 s20, s75, 1
	s_and_saveexec_b64 s[12:13], s[4:5]
	s_cbranch_execz .LBB0_500
	s_lshl_b32 s44, s20, 2
	s_add_i32 s44, s74, s44
	v_lshl_or_b32 v27, v25, 16, v26
	v_mov_b32_e32 v36, s44
	v_mov_b32_e32 v37, s21
	ds_write_b32 v36, v27
	s_waitcnt vmcnt(0) lgkmcnt(0)

; #define PAIR_XCHG(SLOT, TAG, MINE, OTHER) do { const unsigned tg_ = (seq << 8) | (unsigned)(TAG); if (lane == 0) xw[w * 4 + (SLOT)] = ((MINE) << 16) | tg_; \
;             unsigned v_; do { v_ = xw[(w ^ 1) * 4 + (SLOT)]; } while ((v_ & 0xffffu) != tg_); OTHER = v_ >> 16; } while (0)
; __device__ __forceinline__ void attn_item(const Ptrs& P, unsigned char* lds, int b, int tq0, int tid) {
;     ...
;         unsigned th = 0u;
;     ...
;             const unsigned cand = th | (1u << bit); unsigned cnt = 0, oth;
; #pragma unroll
;             for (int k = 0; k < 4; ++k) if (16 * k < nact) {
; #pragma unroll
;                 for (int r = 16 * k; r < 16 * k + 16; ++r) cnt += (unsigned)__popcll(__ballot(k2[r] >= cand)); }
;             PAIR_XCHG(bit & 1, 1 + bit, cnt, oth);
;             cnt += oth;
;             if (cnt >= 256u) th = cand;
;             if (cnt == 256u) break;
;         }
;         unsigned cg = 0, ce = 0;
; #pragma unroll
;         for (int k = 0; k < 4; ++k) if (16 * k < nact) {
; #pragma unroll
;             for (int r = 16 * k; r < 16 * k + 16; ++r) { cg += (k2[r] > th) ? 1u : 0u; ce += (k2[r] == th) ? 1u : 0u; } }
.LBB0_501:
	v_mov_b64_e32 v[36:37], s[20:21]
	ds_read_b32 v27, v36
	s_waitcnt vmcnt(0) lgkmcnt(0)
	v_cmp_eq_u32_sdwa s[44:45], v27, v26 src0_sel:WORD_0 src1_sel:DWORD
	s_or_b64 s[12:13], s[44:45], s[12:13]
	s_andn2_b64 exec, exec, s[12:13]
	s_cbranch_execnz .LBB0_501
	s_or_b64 exec, exec, s[12:13]
	v_add_u32_sdwa v25, v27, v25 dst_sel:DWORD dst_unused:UNUSED_PAD src0_sel:WORD_1 src1_sel:DWORD
	s_movk_i32 s12, 0xff
	v_cmp_lt_u32_e64 s[12:13], s12, v25
	s_nop 1
	v_cndmask_b32_e64 v5, v5, v24, s[12:13]
	s_movk_i32 s12, 0x100
	v_cmp_eq_u32_e64 s[12:13], s12, v25
	v_sub_co_u32_e64 v24, s[44:45], s75, 1
	s_or_b64 s[12:13], s[12:13], s[44:45]
	s_and_b64 s[12:13], exec, s[12:13]
	s_or_b64 s[72:73], s[12:13], s[72:73]
	v_readfirstlane_b32 s75, v24
	s_andn2_b64 exec, exec, s[72:73]
	s_cbranch_execnz .LBB0_490
	s_nop 0
	s_nop 0
	s_nop 0
	s_nop 0
	s_or_b64 exec, exec, s[72:73]
	v_mov_b32_e32 v25, 0
	v_mov_b32_e32 v26, 0
	s_and_saveexec_b64 s[44:45], s[18:19]
	s_cbranch_execz .LBB0_507
	v_cmp_gt_u32_e64 s[12:13], v95, v5
	s_nop 1
	v_cndmask_b32_e64 v24, 0, 1, s[12:13]
	v_cmp_gt_u32_e64 s[12:13], v6, v5
	s_nop 1
	v_addc_co_u32_e64 v24, s[12:13], 0, v24, s[12:13]
	v_cmp_eq_u32_e64 s[12:13], v95, v5
	s_nop 1
	v_cndmask_b32_e64 v25, 0, 1, s[12:13]
	v_cmp_eq_u32_e64 s[12:13], v6, v5
	s_nop 1
	v_addc_co_u32_e64 v25, s[12:13], 0, v25, s[12:13]
	v_cmp_gt_u32_e64 s[12:13], v94, v5
	s_nop 1
	v_cndmask_b32_e64 v26, 0, 1, s[12:13]
	v_cmp_eq_u32_e64 s[12:13], v94, v5
	s_nop 1
	v_cndmask_b32_e64 v27, 0, 1, s[12:13]
	v_cmp_gt_u32_e64 s[12:13], v93, v5
	s_nop 1
	v_addc_co_u32_e64 v24, s[12:13], v24, v26, s[12:13]
	v_cmp_eq_u32_e64 s[12:13], v93, v5
	s_nop 1
	v_addc_co_u32_e64 v25, s[12:13], v25, v27, s[12:13]
	v_cmp_gt_u32_e64 s[12:13], v92, v5
	s_nop 1
	v_cndmask_b32_e64 v26, 0, 1, s[12:13]
	v_cmp_eq_u32_e64 s[12:13], v92, v5
	s_nop 1
	v_cndmask_b32_e64 v27, 0, 1, s[12:13]
	v_cmp_gt_u32_e64 s[12:13], v91, v5
	s_nop 1
	v_addc_co_u32_e64 v24, s[12:13], v24, v26, s[12:13]
	v_cmp_eq_u32_e64 s[12:13], v91, v5
	s_nop 1
	v_addc_co_u32_e64 v25, s[12:13], v25, v27, s[12:13]
	v_cmp_gt_u32_e64 s[12:13], v90, v5
	s_nop 1
	v_cndmask_b32_e64 v26, 0, 1, s[12:13]
	v_cmp_eq_u32_e64 s[12:13], v90, v5
	s_nop 1
	v_cndmask_b32_e64 v27, 0, 1, s[12:13]
	v_cmp_gt_u32_e64 s[12:13], v89, v5
	s_nop 1
	v_addc_co_u32_e64 v24, s[12:13], v24, v26, s[12:13]
	v_cmp_eq_u32_e64 s[12:13], v89, v5
	s_nop 1
	v_addc_co_u32_e64 v25, s[12:13], v25, v27, s[12:13]
	v_cmp_gt_u32_e64 s[12:13], v88, v5
	s_nop 1
	v_cndmask_b32_e64 v26, 0, 1, s[12:13]
	v_cmp_eq_u32_e64 s[12:13], v88, v5
	s_nop 1
	v_cndmask_b32_e64 v27, 0, 1, s[12:13]
	v_cmp_gt_u32_e64 s[12:13], v87, v5
	s_nop 1
	v_addc_co_u32_e64 v24, s[12:13], v24, v26, s[12:13]
	v_cmp_eq_u32_e64 s[12:13], v87, v5
	s_nop 1
	v_addc_co_u32_e64 v25, s[12:13], v25, v27, s[12:13]
	v_cmp_gt_u32_e64 s[12:13], v86, v5
	s_nop 1
	v_cndmask_b32_e64 v26, 0, 1, s[12:13]
	v_cmp_eq_u32_e64 s[12:13], v86, v5
	s_nop 1
	v_cndmask_b32_e64 v27, 0, 1, s[12:13]
	v_cmp_gt_u32_e64 s[12:13], v85, v5
	s_nop 1
	v_addc_co_u32_e64 v24, s[12:13], v24, v26, s[12:13]
	v_cmp_eq_u32_e64 s[12:13], v85, v5
	s_nop 1
	v_addc_co_u32_e64 v25, s[12:13], v25, v27, s[12:13]
	v_cmp_gt_u32_e64 s[12:13], v84, v5
	s_nop 1
	v_cndmask_b32_e64 v26, 0, 1, s[12:13]
	v_cmp_eq_u32_e64 s[12:13], v84, v5
	s_nop 1
	v_cndmask_b32_e64 v27, 0, 1, s[12:13]
	v_cmp_gt_u32_e64 s[12:13], v83, v5
	s_nop 1
	v_addc_co_u32_e64 v24, s[12:13], v24, v26, s[12:13]
	v_cmp_eq_u32_e64 s[12:13], v83, v5
	s_nop 1
	v_addc_co_u32_e64 v25, s[12:13], v25, v27, s[12:13]
	v_cmp_gt_u32_e64 s[12:13], v82, v5
	s_nop 1
	v_cndmask_b32_e64 v26, 0, 1, s[12:13]
	v_cmp_eq_u32_e64 s[12:13], v82, v5
	s_nop 1
	v_cndmask_b32_e64 v27, 0, 1, s[12:13]
	v_cmp_gt_u32_e64 s[12:13], v81, v5
	s_nop 1
	v_addc_co_u32_e64 v26, s[12:13], v24, v26, s[12:13]
	v_cmp_eq_u32_e64 s[12:13], v81, v5
	s_nop 1
	v_addc_co_u32_e64 v25, s[12:13], v25, v27, s[12:13]
	s_or_b64 exec, exec, s[44:45]
	s_and_saveexec_b64 s[44:45], s[16:17]
	s_cbranch_execnz .LBB0_508

; #define PAIR_XCHG(SLOT, TAG, MINE, OTHER) do { const unsigned tg_ = (seq << 8) | (unsigned)(TAG); if (lane == 0) xw[w * 4 + (SLOT)] = ((MINE) << 16) | tg_; \
;             unsigned v_; do { v_ = xw[(w ^ 1) * 4 + (SLOT)]; } while ((v_ & 0xffffu) != tg_); OTHER = v_ >> 16; } while (0)
; __device__ __forceinline__ void attn_item(const Ptrs& P, unsigned char* lds, int b, int tq0, int tid) {
;     ...
;         const unsigned ig = wave_incl_scan(cg, lane), ie = wave_incl_scan(ce, lane);
;         const unsigned ngt = (unsigned)__builtin_amdgcn_readlane((int)ig, 63), neq = (unsigned)__builtin_amdgcn_readlane((int)ie, 63);
;         unsigned ogt, oeq;
;         PAIR_XCHG(2, 40, ngt, ogt); PAIR_XCHG(3, 41, neq, oeq);
.LBB0_511:
	s_or_b64 exec, exec, s[44:45]
	v_add_u32_dpp v24, v26, v26 row_shr:1 row_mask:0xf bank_mask:0xf bound_ctrl:1
	s_nop 1
	v_add_u32_dpp v24, v24, v24 row_shr:2 row_mask:0xf bank_mask:0xf bound_ctrl:1
	s_nop 1
	v_add_u32_dpp v24, v24, v24 row_shr:4 row_mask:0xf bank_mask:0xf bound_ctrl:1
	s_nop 1
	v_add_u32_dpp v24, v24, v24 row_shr:8 row_mask:0xf bank_mask:0xf bound_ctrl:1
	s_nop 0
	v_readlane_b32 s12, v24, 15
	v_readlane_b32 s13, v24, 31
	v_readlane_b32 s20, v24, 47
	v_mov_b32_e32 v27, s12
	v_cndmask_b32_e64 v27, v27, 0, s[6:7]
	v_add_u32_e32 v24, v27, v24
	v_mov_b32_e32 v27, s13
	v_mov_b32_e32 v29, s20
	v_cndmask_b32_e64 v27, 0, v27, s[8:9]
	v_cndmask_b32_e64 v29, 0, v29, s[10:11]
	v_add3_u32 v27, v24, v27, v29
	v_add_u32_dpp v24, v25, v25 row_shr:1 row_mask:0xf bank_mask:0xf bound_ctrl:1
	v_readlane_b32 s45, v27, 63
	s_nop 0
	v_add_u32_dpp v24, v24, v24 row_shr:2 row_mask:0xf bank_mask:0xf bound_ctrl:1
	s_nop 1
	v_add_u32_dpp v24, v24, v24 row_shr:4 row_mask:0xf bank_mask:0xf bound_ctrl:1
	s_nop 1
	v_add_u32_dpp v24, v24, v24 row_shr:8 row_mask:0xf bank_mask:0xf bound_ctrl:1
	s_nop 0
	v_readlane_b32 s12, v24, 15
	v_readlane_b32 s13, v24, 31
	v_readlane_b32 s20, v24, 47
	v_mov_b32_e32 v29, s12
	v_cndmask_b32_e64 v29, v29, 0, s[6:7]
	v_add_u32_e32 v24, v29, v24
	v_mov_b32_e32 v29, s13
	v_mov_b32_e32 v36, s20
	v_cndmask_b32_e64 v29, 0, v29, s[8:9]
	v_cndmask_b32_e64 v36, 0, v36, s[10:11]
	v_add3_u32 v29, v24, v29, v36
	v_or_b32_e32 v36, 40, v1
	v_readlane_b32 s44, v29, 63
	s_and_saveexec_b64 s[12:13], s[4:5]
	s_cbranch_execz .LBB0_513
	s_add_i32 s74, s74, 8
	v_lshl_or_b32 v24, s45, 16, v36
	v_mov_b32_e32 v38, s74
	v_mov_b32_e32 v39, s21
	ds_write_b32 v38, v24
	s_waitcnt vmcnt(0) lgkmcnt(0)

; #define PAIR_XCHG(SLOT, TAG, MINE, OTHER) do { const unsigned tg_ = (seq << 8) | (unsigned)(TAG); if (lane == 0) xw[w * 4 + (SLOT)] = ((MINE) << 16) | tg_; \
;             unsigned v_; do { v_ = xw[(w ^ 1) * 4 + (SLOT)]; } while ((v_ & 0xffffu) != tg_); OTHER = v_ >> 16; } while (0)
; __device__ __forceinline__ void attn_item(const Ptrs& P, unsigned char* lds, int b, int tq0, int tid) {
;     ...
;         PAIR_XCHG(2, 40, ngt, ogt); PAIR_XCHG(3, 41, neq, oeq);
.LBB0_514:
	v_mov_b64_e32 v[38:39], s[20:21]
	ds_read_b32 v24, v38
	s_waitcnt vmcnt(0) lgkmcnt(0)
	v_cmp_eq_u32_sdwa s[74:75], v24, v36 src0_sel:WORD_0 src1_sel:DWORD
	s_or_b64 s[12:13], s[74:75], s[12:13]
	s_andn2_b64 exec, exec, s[12:13]
	s_cbranch_execnz .LBB0_514
	s_or_b64 exec, exec, s[12:13]
	v_or_b32_e32 v36, 41, v1
	s_and_saveexec_b64 s[12:13], s[4:5]
	s_cbranch_execz .LBB0_517
	s_lshl_b32 s20, s83, 2
	s_add_i32 s20, s20, 0
	s_add_i32 s20, s20, 0x2400c
	v_lshl_or_b32 v37, s44, 16, v36
	v_mov_b32_e32 v38, s20
	v_mov_b32_e32 v39, s21
	ds_write_b32 v38, v37
	s_waitcnt vmcnt(0) lgkmcnt(0)

; #define PAIR_XCHG(SLOT, TAG, MINE, OTHER) do { const unsigned tg_ = (seq << 8) | (unsigned)(TAG); if (lane == 0) xw[w * 4 + (SLOT)] = ((MINE) << 16) | tg_; \
;             unsigned v_; do { v_ = xw[(w ^ 1) * 4 + (SLOT)]; } while ((v_ & 0xffffu) != tg_); OTHER = v_ >> 16; } while (0)
; __device__ __forceinline__ void attn_item(const Ptrs& P, unsigned char* lds, int b, int tq0, int tid) {
;     ...
;         PAIR_XCHG(2, 40, ngt, ogt); PAIR_XCHG(3, 41, neq, oeq);
;         const unsigned tot_gt = ngt + ogt, quota = 256u - tot_gt;
;         unsigned pos_g = (hs ? ogt : 0u) + ig - cg, pos_e = (hs ? oeq : 0u) + ie - ce;
;         const bool any_eq = (neq + oeq) != 0u;
; #pragma unroll
;         for (int k = 0; k < 4; ++k) if (16 * k < nact) {
; #pragma unroll
;             for (int r = 16 * k; r < 16 * k + 16; ++r) { const unsigned short idx = (unsigned short)(64 * (2 * r + hs) + lane);
;                 if (k2[r] > th) { sel[qs * 256 + pos_g] = idx; ++pos_g; }
;                 if (any_eq) { if (k2[r] == th) { if (pos_e < quota) sel[qs * 256 + tot_gt + pos_e] = idx; ++pos_e; } } } }
.LBB0_518:
	v_mov_b64_e32 v[38:39], s[20:21]
	ds_read_b32 v37, v38
	s_waitcnt vmcnt(0) lgkmcnt(0)
	v_cmp_eq_u32_sdwa s[74:75], v37, v36 src0_sel:WORD_0 src1_sel:DWORD
	s_or_b64 s[12:13], s[74:75], s[12:13]
	s_andn2_b64 exec, exec, s[12:13]
	s_cbranch_execnz .LBB0_518
	s_or_b64 exec, exec, s[12:13]
	s_cmp_eq_u32 s64, 0
	v_lshrrev_b32_e32 v36, 16, v24
	s_cselect_b64 s[12:13], -1, 0
	v_lshrrev_b32_e32 v37, 16, v37
	v_add_u32_e32 v38, s45, v36
	v_cndmask_b32_e64 v36, v36, 0, s[12:13]
	v_sub_u32_e32 v26, v27, v26
	v_add_u32_e32 v27, v36, v26
	v_cndmask_b32_e64 v26, v37, 0, s[12:13]
	v_sub_u32_e32 v25, v29, v25
	s_lshl_b32 s20, s65, 9
	v_add_u32_e32 v25, v26, v25
	v_sub_u32_e32 v26, 0, v37
	s_add_i32 s20, s20, 0
	v_cmp_ne_u32_e64 s[12:13], s44, v26
	s_lshl_b32 s44, s64, 6
	s_add_i32 s20, s20, 0x21000
	v_sub_u32_e32 v24, 0x100, v38
	v_lshl_add_u32 v26, v38, 1, s20
	v_or_b32_e32 v29, s44, v179
	s_and_saveexec_b64 s[74:75], s[18:19]
	s_cbranch_execz .LBB0_715
	v_cmp_gt_u32_e64 s[18:19], v6, v5
	s_and_saveexec_b64 s[44:45], s[18:19]
	v_lshl_add_u32 v36, v27, 1, s20
	v_add_u32_e32 v27, 1, v27
	ds_write_b16 v36, v29
	s_or_b64 exec, exec, s[44:45]
	v_cmp_eq_u32_e64 s[18:19], v6, v5
	s_and_b64 s[18:19], s[12:13], s[18:19]
	s_and_saveexec_b64 s[44:45], s[18:19]
	s_cbranch_execz .LBB0_526
	v_cmp_lt_u32_e64 s[18:19], v25, v24
	s_and_saveexec_b64 s[78:79], s[18:19]
	v_lshl_add_u32 v6, v25, 1, v26
	ds_write_b16 v6, v29
	s_or_b64 exec, exec, s[78:79]
	v_add_u32_e32 v25, 1, v25

; #define PAIR_XCHG(SLOT, TAG, MINE, OTHER) do { const unsigned tg_ = (seq << 8) | (unsigned)(TAG); if (lane == 0) xw[w * 4 + (SLOT)] = ((MINE) << 16) | tg_; \
;             unsigned v_; do { v_ = xw[(w ^ 1) * 4 + (SLOT)]; } while ((v_ & 0xffffu) != tg_); OTHER = v_ >> 16; } while (0)
; __device__ __forceinline__ void attn_item(const Ptrs& P, unsigned char* lds, int b, int tq0, int tid) {
;     ...
;         { unsigned dn_; PAIR_XCHG(0, 42, 0u, dn_); (void)dn_; }
.LBB0_908:
	s_or_b64 exec, exec, s[14:15]
	v_or_b32_e32 v0, 42, v1
	s_and_saveexec_b64 s[12:13], s[4:5]
	s_cbranch_execz .LBB0_910
	s_lshl_b32 s14, s83, 2
	s_add_i32 s14, s14, 0
	s_add_i32 s14, s14, 0x24000
	v_mov_b32_e32 v2, s14
	v_mov_b32_e32 v3, s21
	ds_write_b32 v2, v0
	s_waitcnt vmcnt(0) lgkmcnt(0)

; #define PAIR_XCHG(SLOT, TAG, MINE, OTHER) do { const unsigned tg_ = (seq << 8) | (unsigned)(TAG); if (lane == 0) xw[w * 4 + (SLOT)] = ((MINE) << 16) | tg_; \
;             unsigned v_; do { v_ = xw[(w ^ 1) * 4 + (SLOT)]; } while ((v_ & 0xffffu) != tg_); OTHER = v_ >> 16; } while (0)
; __device__ __forceinline__ void attn_item(const Ptrs& P, unsigned char* lds, int b, int tq0, int tid) {
;     ...
;         { unsigned dn_; PAIR_XCHG(0, 42, 0u, dn_); (void)dn_; }
.LBB0_911:
	v_mov_b64_e32 v[2:3], s[72:73]
	ds_read_b32 v1, v2
	s_waitcnt vmcnt(0) lgkmcnt(0)
	v_cmp_eq_u32_sdwa s[14:15], v1, v0 src0_sel:WORD_0 src1_sel:DWORD
	s_or_b64 s[12:13], s[14:15], s[12:13]
	s_andn2_b64 exec, exec, s[12:13]
	s_cbranch_execnz .LBB0_911
	s_or_b64 exec, exec, s[12:13]

; __device__ __forceinline__ void attn_item(const Ptrs& P, unsigned char* lds, int b, int tq0, int tid) {
;     ...
;     {
;         const bf16_t* qlp = P.QL + (rowb + tq) * 4096 + r16 * 256 + 8 * g;
; #pragma unroll
;         for (int ks = 0; ks < 8; ++ks) Af[ks] = *(const bf16x8*)(qlp + 32 * ks);
;     }
;     bf16_t* stw = stg + w * 32 * SP;
;     bf16_t* Pw = (bf16_t*)(l2 + 2048) + w * 16 * 40;
;     volatile unsigned* xa = (volatile unsigned*)(lds + 147456);
;     const unsigned aseq = (xa[40 + w] + 1u) & 0xffffu; if (lane == 0) xa[40 + w] = aseq;
.LBB0_921:
	s_or_b64 exec, exec, s[14:15]
	v_add_u32_e32 v220, v32, v124
	v_add_u32_e32 v164, s81, v220
	v_lshlrev_b64 v[0:1], 13, v[164:165]
	v_lshl_add_u64 v[184:185], s[76:77], 0, v[0:1]
	v_mov_b32_e32 v181, v165
	v_lshl_add_u64 v[0:1], v[184:185], 0, v[180:181]
	v_lshlrev_b32_e32 v164, 1, v166
	v_lshl_add_u64 v[28:29], v[0:1], 0, v[164:165]
	global_load_dwordx4 v[0:3], v[28:29], off
	global_load_dwordx4 v[4:7], v[28:29], off offset:64
	global_load_dwordx4 v[8:11], v[28:29], off offset:128
	global_load_dwordx4 v[12:15], v[28:29], off offset:192
	global_load_dwordx4 v[16:19], v[28:29], off offset:256
	global_load_dwordx4 v[20:23], v[28:29], off offset:320
	global_load_dwordx4 v[24:27], v[28:29], off offset:384
	s_nop 0
	global_load_dwordx4 v[28:31], v[28:29], off offset:448
	s_lshl_b32 s12, s62, 2
	s_add_i32 s16, s12, 0
	s_add_i32 s20, s16, 0x240a0
	v_mov_b64_e32 v[34:35], s[20:21]
	ds_read_b32 v33, v34
	s_waitcnt vmcnt(0) lgkmcnt(0)
	v_add_u32_e32 v33, 1, v33
	v_and_b32_e32 v218, 0xffff, v33
	s_and_saveexec_b64 s[12:13], s[4:5]
	s_cbranch_execz .LBB0_923
	v_mov_b64_e32 v[34:35], s[20:21]
	ds_write_b32 v34, v218
	s_waitcnt vmcnt(0) lgkmcnt(0)

; __device__ __forceinline__ void attn_item(const Ptrs& P, unsigned char* lds, int b, int tq0, int tid) {
;     ...
;     {
;         float* cmb = (float*)stw;
; #pragma unroll
;         for (int dt = 0; dt < 8; ++dt)
; #pragma unroll
;             for (int j = 0; j < 4; ++j) cmb[(dt * 4 + j) * 64 + lane] = half ? oacc[dt][j] : oacc[8 + dt][j];
; #pragma unroll
;         for (int j = 0; j < 4; ++j) { cmb[2048 + j * 64 + lane] = mrun[j]; cmb[2304 + j * 64 + lane] = lrun[j]; }
;         asm volatile("s_waitcnt lgkmcnt(0)" ::: "memory");
;         if (lane == 0) xa[48 + w] = aseq;
.LBB0_928:
	v_lshl_add_u32 v0, v179, 2, s12
	v_cmp_eq_u32_e64 s[12:13], 0, v219
	s_nop 1
	v_cndmask_b32_e64 v3, v109, v149, s[12:13]
	v_cndmask_b32_e64 v4, v108, v148, s[12:13]
	v_cndmask_b32_e64 v1, v111, v151, s[12:13]
	v_cndmask_b32_e64 v2, v110, v150, s[12:13]
	ds_write2st64_b32 v0, v4, v3 offset1:1
	ds_write2st64_b32 v0, v2, v1 offset0:2 offset1:3
	v_cndmask_b32_e64 v3, v101, v137, s[12:13]
	v_cndmask_b32_e64 v4, v100, v136, s[12:13]
	v_cndmask_b32_e64 v1, v103, v139, s[12:13]
	v_cndmask_b32_e64 v2, v102, v138, s[12:13]
	ds_write2st64_b32 v0, v4, v3 offset0:4 offset1:5
	ds_write2st64_b32 v0, v2, v1 offset0:6 offset1:7
	v_cndmask_b32_e64 v3, v85, v125, s[12:13]
	v_cndmask_b32_e64 v4, v84, v124, s[12:13]
	v_cndmask_b32_e64 v1, v87, v127, s[12:13]
	v_cndmask_b32_e64 v2, v86, v126, s[12:13]
	ds_write2st64_b32 v0, v4, v3 offset0:8 offset1:9
	ds_write2st64_b32 v0, v2, v1 offset0:10 offset1:11
	v_cndmask_b32_e64 v3, v69, v113, s[12:13]
	v_cndmask_b32_e64 v4, v68, v112, s[12:13]
	v_cndmask_b32_e64 v1, v71, v115, s[12:13]
	v_cndmask_b32_e64 v2, v70, v114, s[12:13]
	ds_write2st64_b32 v0, v4, v3 offset0:12 offset1:13
	ds_write2st64_b32 v0, v2, v1 offset0:14 offset1:15
	v_cndmask_b32_e64 v3, v49, v105, s[12:13]
	v_cndmask_b32_e64 v4, v48, v104, s[12:13]
	v_cndmask_b32_e64 v1, v51, v107, s[12:13]
	v_cndmask_b32_e64 v2, v50, v106, s[12:13]
	ds_write2st64_b32 v0, v4, v3 offset0:16 offset1:17
	ds_write2st64_b32 v0, v2, v1 offset0:18 offset1:19
	v_cndmask_b32_e64 v3, v41, v97, s[12:13]
	v_cndmask_b32_e64 v4, v40, v96, s[12:13]
	v_cndmask_b32_e64 v1, v43, v99, s[12:13]
	v_cndmask_b32_e64 v2, v42, v98, s[12:13]
	ds_write2st64_b32 v0, v4, v3 offset0:20 offset1:21
	ds_write2st64_b32 v0, v2, v1 offset0:22 offset1:23
	v_cndmask_b32_e64 v3, v37, v81, s[12:13]
	v_cndmask_b32_e64 v4, v36, v80, s[12:13]
	v_cndmask_b32_e64 v1, v39, v83, s[12:13]
	v_cndmask_b32_e64 v2, v38, v82, s[12:13]
	ds_write2st64_b32 v0, v4, v3 offset0:24 offset1:25
	ds_write2st64_b32 v0, v2, v1 offset0:26 offset1:27
	v_cndmask_b32_e64 v3, v33, v45, s[12:13]
	v_cndmask_b32_e64 v4, v32, v44, s[12:13]
	v_cndmask_b32_e64 v1, v35, v47, s[12:13]
	v_cndmask_b32_e64 v2, v34, v46, s[12:13]
	ds_write2st64_b32 v0, v4, v3 offset0:28 offset1:29
	ds_write2st64_b32 v0, v2, v1 offset0:30 offset1:31
	ds_write2st64_b32 v0, v164, v233 offset0:32 offset1:33
	ds_write2st64_b32 v0, v191, v190 offset0:36 offset1:37
	ds_write2st64_b32 v0, v234, v235 offset0:34 offset1:35
	ds_write2st64_b32 v0, v187, v186 offset0:38 offset1:39
	s_waitcnt lgkmcnt(0)
	s_and_saveexec_b64 s[14:15], s[4:5]
	s_cbranch_execz .LBB0_930
	s_addk_i32 s16, 0xc0
	v_mov_b32_e32 v0, s16
	v_mov_b32_e32 v1, s21
	ds_write_b32 v0, v218
	s_waitcnt vmcnt(0) lgkmcnt(0)

; __device__ __forceinline__ unsigned cvt_pk_bf16(float lo, float hi) { unsigned r; asm volatile("v_cvt_pk_bf16_f32 %0, %1, %2" : "=v"(r) : "v"(lo), "v"(hi)); return r; }
; __device__ __forceinline__ void attn_item(const Ptrs& P, unsigned char* lds, int b, int tq0, int tid) {
;     ...
;         while (xa[48 + (w ^ 1)] != aseq) { }
;         const float* pc = (const float*)(stg + (w ^ 1) * 32 * SP);
;         float wa[4], wb[4];
; #pragma unroll
;         for (int j = 0; j < 4; ++j) { const float mo = pc[2048 + j * 64 + lane], lo = pc[2304 + j * 64 + lane];
;             const float mm = fmaxf(mrun[j], mo); const float ea = __expf(mrun[j] - mm), eb = __expf(mo - mm);
;             const float inv = 1.f / (lrun[j] * ea + lo * eb); wa[j] = ea * inv; wb[j] = eb * inv; }
;         bf16_t* op = P.QL + (rowb + tq) * 4096;
; #pragma unroll
;         for (int dt = 0; dt < 8; ++dt)
; #pragma unroll
;             for (int j = 0; j < 4; ++j) { const float v = (half ? oacc[8 + dt][j] : oacc[dt][j]) * wa[j] + pc[(dt * 4 + j) * 64 + lane] * wb[j];
;                 op[(4 * g + j) * 256 + 16 * (8 * half + dt) + r16] = (bf16_t)(cvt_pk_bf16(v, 0.f) & 0xffffu); }
.LBB0_931:
	v_mov_b64_e32 v[0:1], s[20:21]
	ds_read_b32 v0, v0
	s_waitcnt vmcnt(0) lgkmcnt(0)
	v_cmp_eq_u32_e32 vcc, v0, v218
	s_or_b64 s[14:15], vcc, s[14:15]
	s_andn2_b64 exec, exec, s[14:15]
	s_cbranch_execnz .LBB0_931
	s_or_b64 exec, exec, s[14:15]
	s_mulk_i32 s16, 0x4200
	v_add_u32_e32 v8, s16, v203
	ds_read2st64_b32 v[0:1], v8 offset1:32
	v_max_f32_e32 v4, v164, v164
	ds_read2st64_b32 v[2:3], v8 offset0:35 offset1:36
	v_cndmask_b32_e64 v17, v149, v109, s[12:13]
	s_waitcnt lgkmcnt(1)
	v_max_f32_e32 v5, v1, v1
	v_max_f32_e32 v4, v4, v5
	v_sub_f32_e32 v1, v1, v4
	v_sub_f32_e32 v5, v164, v4
	v_mul_f32_e32 v1, 0x3fb8aa3b, v1
	v_mul_f32_e32 v4, 0x3fb8aa3b, v5
	v_exp_f32_e32 v1, v1
	v_exp_f32_e32 v9, v4
	ds_read2st64_b32 v[4:5], v8 offset0:37 offset1:38
	ds_read_b32 v10, v8 offset:9984
	ds_read2st64_b32 v[6:7], v8 offset0:33 offset1:34
	s_waitcnt lgkmcnt(3)
	v_mul_f32_e32 v3, v3, v1
	v_fmac_f32_e32 v3, v191, v9
	v_div_scale_f32 v11, s[14:15], v3, v3, 1.0
	v_rcp_f32_e32 v12, v11
	s_nop 0
	v_fma_f32 v13, -v11, v12, 1.0
	v_fmac_f32_e32 v12, v13, v12
	v_div_scale_f32 v13, vcc, 1.0, v3, 1.0
	v_mul_f32_e32 v14, v13, v12
	v_fma_f32 v15, -v11, v14, v13
	v_fmac_f32_e32 v14, v15, v12
	v_fma_f32 v11, -v11, v14, v13
	s_waitcnt lgkmcnt(0)
	v_max_f32_e32 v13, v6, v6
	v_max_f32_e32 v15, v233, v233
	v_max_f32_e32 v13, v15, v13
	v_sub_f32_e32 v6, v6, v13
	v_sub_f32_e32 v15, v233, v13
	v_mul_f32_e32 v6, 0x3fb8aa3b, v6
	v_mul_f32_e32 v15, 0x3fb8aa3b, v15
	v_exp_f32_e32 v6, v6
	v_exp_f32_e32 v13, v15
	v_div_fmas_f32 v11, v11, v12, v14
	v_div_fixup_f32 v3, v11, v3, 1.0
	v_mul_f32_e32 v4, v4, v6
	v_fmac_f32_e32 v4, v190, v13
	v_div_scale_f32 v12, s[14:15], v4, v4, 1.0
	v_rcp_f32_e32 v14, v12
	v_mul_f32_e32 v9, v9, v3
	v_mul_f32_e32 v3, v1, v3
	v_mul_f32_e32 v0, v0, v3
	v_fma_f32 v1, -v12, v14, 1.0
	v_fmac_f32_e32 v14, v1, v14
	v_div_scale_f32 v1, vcc, 1.0, v4, 1.0
	v_mul_f32_e32 v11, v1, v14
	v_fma_f32 v15, -v12, v11, v1
	v_fmac_f32_e32 v11, v15, v14
	v_fma_f32 v1, -v12, v11, v1
	v_max_f32_e32 v12, v7, v7
	v_max_f32_e32 v15, v234, v234
	v_max_f32_e32 v12, v15, v12
	v_sub_f32_e32 v7, v7, v12
	v_sub_f32_e32 v15, v234, v12
	v_mul_f32_e32 v7, 0x3fb8aa3b, v7
	v_mul_f32_e32 v15, 0x3fb8aa3b, v15
	v_exp_f32_e32 v7, v7
	v_exp_f32_e32 v12, v15
	v_div_fmas_f32 v1, v1, v14, v11
	v_div_fixup_f32 v1, v1, v4, 1.0
	v_mul_f32_e32 v5, v5, v7
	v_fmac_f32_e32 v5, v187, v12
	v_div_scale_f32 v11, s[14:15], v5, v5, 1.0
	v_rcp_f32_e32 v14, v11
	v_mul_f32_e32 v4, v13, v1
	v_mul_f32_e32 v6, v6, v1
	v_fma_f32 v1, -v11, v14, 1.0
	v_fmac_f32_e32 v14, v1, v14
	v_div_scale_f32 v1, vcc, 1.0, v5, 1.0
	v_mul_f32_e32 v13, v1, v14
	v_fma_f32 v15, -v11, v13, v1
	v_fmac_f32_e32 v13, v15, v14
	v_fma_f32 v1, -v11, v13, v1
	v_max_f32_e32 v11, v2, v2
	v_max_f32_e32 v15, v235, v235
	v_max_f32_e32 v11, v15, v11
	v_sub_f32_e32 v2, v2, v11
	v_sub_f32_e32 v15, v235, v11
	v_mul_f32_e32 v2, 0x3fb8aa3b, v2
	v_mul_f32_e32 v15, 0x3fb8aa3b, v15
	v_exp_f32_e32 v2, v2
	v_exp_f32_e32 v11, v15
	v_div_fmas_f32 v1, v1, v14, v13
	v_div_fixup_f32 v1, v1, v5, 1.0
	v_mul_f32_e32 v10, v10, v2
	v_fmac_f32_e32 v10, v186, v11
	v_div_scale_f32 v13, s[14:15], v10, v10, 1.0
	v_rcp_f32_e32 v14, v13
	v_mul_f32_e32 v5, v12, v1
	v_mul_f32_e32 v7, v7, v1
	v_fma_f32 v1, -v13, v14, 1.0
	v_fmac_f32_e32 v14, v1, v14
	v_div_scale_f32 v1, vcc, 1.0, v10, 1.0
	v_mul_f32_e32 v12, v1, v14
	v_fma_f32 v15, -v13, v12, v1
	v_fmac_f32_e32 v12, v15, v14
	v_cndmask_b32_e64 v15, v148, v108, s[12:13]
	v_fmac_f32_e32 v0, v15, v9
	v_cvt_pk_bf16_f32 v15, v0, v165
	ds_read_b32 v16, v8 offset:256
	v_fma_f32 v13, -v13, v12, v1
	v_or_b32_e32 v1, v181, v204
	v_lshlrev_b32_e32 v164, 1, v1
	v_lshl_add_u64 v[0:1], v[184:185], 0, v[164:165]
	global_store_short v[0:1], v15, off
	s_waitcnt lgkmcnt(0)
	v_mul_f32_e32 v15, v6, v16
	v_fmac_f32_e32 v15, v17, v4
	v_cvt_pk_bf16_f32 v15, v15, v165
	ds_read_b32 v16, v8 offset:512
	v_div_fmas_f32 v12, v13, v14, v12
	v_div_fixup_f32 v10, v12, v10, 1.0
	v_cndmask_b32_e64 v12, v150, v110, s[12:13]
	global_store_short v[0:1], v15, off offset:512
	s_waitcnt lgkmcnt(0)
	v_mul_f32_e32 v13, v7, v16
	v_fmac_f32_e32 v13, v12, v5
	v_cvt_pk_bf16_f32 v12, v13, v165
	ds_read_b32 v13, v8 offset:768
	v_mul_f32_e32 v2, v2, v10
	v_mul_f32_e32 v11, v11, v10
	v_cndmask_b32_e64 v10, v151, v111, s[12:13]
	global_store_short v[0:1], v12, off offset:1024
	s_waitcnt lgkmcnt(0)
	v_mul_f32_e32 v12, v2, v13
	v_fmac_f32_e32 v12, v10, v11
	v_cvt_pk_bf16_f32 v10, v12, v165
	ds_read_b32 v12, v8 offset:1024
	global_store_short v[0:1], v10, off offset:1536
	v_cndmask_b32_e64 v10, v136, v100, s[12:13]
	v_cndmask_b32_e64 v13, v137, v101, s[12:13]
	s_waitcnt lgkmcnt(0)
	v_mul_f32_e32 v12, v3, v12
	v_fmac_f32_e32 v12, v10, v9
	v_cvt_pk_bf16_f32 v10, v12, v165
	ds_read_b32 v12, v8 offset:1280
	global_store_short v[0:1], v10, off offset:32
	s_waitcnt lgkmcnt(0)
	v_mul_f32_e32 v10, v6, v12
	v_fmac_f32_e32 v10, v13, v4
	v_cvt_pk_bf16_f32 v10, v10, v165
	ds_read_b32 v12, v8 offset:1536
	v_cndmask_b32_e64 v13, v138, v102, s[12:13]
	global_store_short v[0:1], v10, off offset:544
	s_waitcnt lgkmcnt(0)
	v_mul_f32_e32 v10, v7, v12
	v_fmac_f32_e32 v10, v13, v5
	v_cvt_pk_bf16_f32 v10, v10, v165
	ds_read_b32 v12, v8 offset:1792
	v_cndmask_b32_e64 v13, v139, v103, s[12:13]
	global_store_short v[0:1], v10, off offset:1056
	s_waitcnt lgkmcnt(0)
	v_mul_f32_e32 v10, v2, v12
	v_fmac_f32_e32 v10, v13, v11
	v_cvt_pk_bf16_f32 v10, v10, v165
	ds_read_b32 v12, v8 offset:2048
	global_store_short v[0:1], v10, off offset:1568
	v_cndmask_b32_e64 v10, v124, v84, s[12:13]
	v_cndmask_b32_e64 v13, v125, v85, s[12:13]
	s_waitcnt lgkmcnt(0)
; __device__ __forceinline__ unsigned cvt_pk_bf16(float lo, float hi) { unsigned r; asm volatile("v_cvt_pk_bf16_f32 %0, %1, %2" : "=v"(r) : "v"(lo), "v"(hi)); return r; }
; __device__ __forceinline__ void attn_item(const Ptrs& P, unsigned char* lds, int b, int tq0, int tid) {
;     ...
;         bf16_t* op = P.QL + (rowb + tq) * 4096;
; #pragma unroll
;         for (int dt = 0; dt < 8; ++dt)
; #pragma unroll
;             for (int j = 0; j < 4; ++j) { const float v = (half ? oacc[8 + dt][j] : oacc[dt][j]) * wa[j] + pc[(dt * 4 + j) * 64 + lane] * wb[j];
;                 op[(4 * g + j) * 256 + 16 * (8 * half + dt) + r16] = (bf16_t)(cvt_pk_bf16(v, 0.f) & 0xffffu); }
	v_mul_f32_e32 v12, v3, v12
	v_fmac_f32_e32 v12, v10, v9
	v_cvt_pk_bf16_f32 v10, v12, v165
	ds_read_b32 v12, v8 offset:2304
	global_store_short v[0:1], v10, off offset:64
	s_waitcnt lgkmcnt(0)
	v_mul_f32_e32 v10, v6, v12
	v_fmac_f32_e32 v10, v13, v4
	v_cvt_pk_bf16_f32 v10, v10, v165
	ds_read_b32 v12, v8 offset:2560
	v_cndmask_b32_e64 v13, v126, v86, s[12:13]
	global_store_short v[0:1], v10, off offset:576
	s_waitcnt lgkmcnt(0)
	v_mul_f32_e32 v10, v7, v12
	v_fmac_f32_e32 v10, v13, v5
	v_cvt_pk_bf16_f32 v10, v10, v165
	ds_read_b32 v12, v8 offset:2816
	v_cndmask_b32_e64 v13, v127, v87, s[12:13]
	global_store_short v[0:1], v10, off offset:1088
	s_waitcnt lgkmcnt(0)
	v_mul_f32_e32 v10, v2, v12
	v_fmac_f32_e32 v10, v13, v11
	v_cvt_pk_bf16_f32 v10, v10, v165
	ds_read_b32 v12, v8 offset:3072
	global_store_short v[0:1], v10, off offset:1600
	v_cndmask_b32_e64 v10, v112, v68, s[12:13]
	v_cndmask_b32_e64 v13, v113, v69, s[12:13]
	s_waitcnt lgkmcnt(0)
	v_mul_f32_e32 v12, v3, v12
	v_fmac_f32_e32 v12, v10, v9
	v_cvt_pk_bf16_f32 v10, v12, v165
	ds_read_b32 v12, v8 offset:3328
	global_store_short v[0:1], v10, off offset:96
	s_waitcnt lgkmcnt(0)
	v_mul_f32_e32 v10, v6, v12
	v_fmac_f32_e32 v10, v13, v4
	v_cvt_pk_bf16_f32 v10, v10, v165
	ds_read_b32 v12, v8 offset:3584
	v_cndmask_b32_e64 v13, v114, v70, s[12:13]
	global_store_short v[0:1], v10, off offset:608
	s_waitcnt lgkmcnt(0)
	v_mul_f32_e32 v10, v7, v12
	v_fmac_f32_e32 v10, v13, v5
	v_cvt_pk_bf16_f32 v10, v10, v165
	ds_read_b32 v12, v8 offset:3840
	v_cndmask_b32_e64 v13, v115, v71, s[12:13]
	global_store_short v[0:1], v10, off offset:1120
	s_waitcnt lgkmcnt(0)
	v_mul_f32_e32 v10, v2, v12
	v_fmac_f32_e32 v10, v13, v11
	v_cvt_pk_bf16_f32 v10, v10, v165
	ds_read_b32 v12, v8 offset:4096
	global_store_short v[0:1], v10, off offset:1632
	v_cndmask_b32_e64 v10, v104, v48, s[12:13]
	v_cndmask_b32_e64 v13, v105, v49, s[12:13]
	s_waitcnt lgkmcnt(0)
	v_mul_f32_e32 v12, v3, v12
	v_fmac_f32_e32 v12, v10, v9
	v_cvt_pk_bf16_f32 v10, v12, v165
	ds_read_b32 v12, v8 offset:4352
	global_store_short v[0:1], v10, off offset:128
	s_waitcnt lgkmcnt(0)
	v_mul_f32_e32 v10, v6, v12
	v_fmac_f32_e32 v10, v13, v4
	v_cvt_pk_bf16_f32 v10, v10, v165
	ds_read_b32 v12, v8 offset:4608
	v_cndmask_b32_e64 v13, v106, v50, s[12:13]
	global_store_short v[0:1], v10, off offset:640
	s_waitcnt lgkmcnt(0)
	v_mul_f32_e32 v10, v7, v12
	v_fmac_f32_e32 v10, v13, v5
	v_cvt_pk_bf16_f32 v10, v10, v165
	ds_read_b32 v12, v8 offset:4864
	v_cndmask_b32_e64 v13, v107, v51, s[12:13]
	global_store_short v[0:1], v10, off offset:1152
	s_waitcnt lgkmcnt(0)
	v_mul_f32_e32 v10, v2, v12
	v_fmac_f32_e32 v10, v13, v11
	v_cvt_pk_bf16_f32 v10, v10, v165
	ds_read_b32 v12, v8 offset:5120
	global_store_short v[0:1], v10, off offset:1664
	v_cndmask_b32_e64 v10, v96, v40, s[12:13]
	v_cndmask_b32_e64 v13, v97, v41, s[12:13]
	s_waitcnt lgkmcnt(0)
	v_mul_f32_e32 v12, v3, v12
	v_fmac_f32_e32 v12, v10, v9
	v_cvt_pk_bf16_f32 v10, v12, v165
	ds_read_b32 v12, v8 offset:5376
	global_store_short v[0:1], v10, off offset:160
	s_waitcnt lgkmcnt(0)
	v_mul_f32_e32 v10, v6, v12
	v_fmac_f32_e32 v10, v13, v4
	v_cvt_pk_bf16_f32 v10, v10, v165
	ds_read_b32 v12, v8 offset:5632
	v_cndmask_b32_e64 v13, v98, v42, s[12:13]
	global_store_short v[0:1], v10, off offset:672
	s_waitcnt lgkmcnt(0)
	v_mul_f32_e32 v10, v7, v12
	v_fmac_f32_e32 v10, v13, v5
	v_cvt_pk_bf16_f32 v10, v10, v165
	ds_read_b32 v12, v8 offset:5888
	v_cndmask_b32_e64 v13, v99, v43, s[12:13]
	global_store_short v[0:1], v10, off offset:1184
	s_waitcnt lgkmcnt(0)
	v_mul_f32_e32 v10, v2, v12
	v_fmac_f32_e32 v10, v13, v11
	v_cvt_pk_bf16_f32 v10, v10, v165
	ds_read_b32 v12, v8 offset:6144
	global_store_short v[0:1], v10, off offset:1696
	v_cndmask_b32_e64 v10, v80, v36, s[12:13]
	v_cndmask_b32_e64 v13, v81, v37, s[12:13]
	s_waitcnt lgkmcnt(0)
	v_mul_f32_e32 v12, v3, v12
	v_fmac_f32_e32 v12, v10, v9
	v_cvt_pk_bf16_f32 v10, v12, v165
	ds_read_b32 v12, v8 offset:6400
	global_store_short v[0:1], v10, off offset:192
	s_waitcnt lgkmcnt(0)
	v_mul_f32_e32 v10, v6, v12
	v_fmac_f32_e32 v10, v13, v4
	v_cvt_pk_bf16_f32 v10, v10, v165
	ds_read_b32 v12, v8 offset:6656
	v_cndmask_b32_e64 v13, v82, v38, s[12:13]
	global_store_short v[0:1], v10, off offset:704
	s_waitcnt lgkmcnt(0)
	v_mul_f32_e32 v10, v7, v12
	v_fmac_f32_e32 v10, v13, v5
	v_cvt_pk_bf16_f32 v10, v10, v165
	ds_read_b32 v12, v8 offset:6912
	v_cndmask_b32_e64 v13, v83, v39, s[12:13]
	global_store_short v[0:1], v10, off offset:1216
	s_waitcnt lgkmcnt(0)
	v_mul_f32_e32 v10, v2, v12
	v_fmac_f32_e32 v10, v13, v11
	v_cvt_pk_bf16_f32 v10, v10, v165
	ds_read_b32 v12, v8 offset:7168
	global_store_short v[0:1], v10, off offset:1728
	v_cndmask_b32_e64 v10, v44, v32, s[12:13]
	s_waitcnt lgkmcnt(0)
	v_mul_f32_e32 v3, v3, v12
	v_fmac_f32_e32 v3, v10, v9
	v_cvt_pk_bf16_f32 v3, v3, v165
	ds_read_b32 v9, v8 offset:7424
	v_cndmask_b32_e64 v10, v45, v33, s[12:13]
	global_store_short v[0:1], v3, off offset:224
	s_waitcnt lgkmcnt(0)
	v_mul_f32_e32 v3, v6, v9
	v_fmac_f32_e32 v3, v10, v4
	v_cvt_pk_bf16_f32 v3, v3, v165
	ds_read_b32 v4, v8 offset:7680
	v_cndmask_b32_e64 v6, v46, v34, s[12:13]
	global_store_short v[0:1], v3, off offset:736
	s_waitcnt lgkmcnt(0)
	v_mul_f32_e32 v3, v7, v4
	v_fmac_f32_e32 v3, v6, v5
	v_cvt_pk_bf16_f32 v3, v3, v165
	ds_read_b32 v4, v8 offset:7936
	v_cndmask_b32_e64 v5, v47, v35, s[12:13]
	s_xor_b64 s[12:13], exec, -1
	global_store_short v[0:1], v3, off offset:1248
	s_waitcnt lgkmcnt(0)
	v_mul_f32_e32 v2, v2, v4
	v_fmac_f32_e32 v2, v5, v11
	v_cvt_pk_bf16_f32 v2, v2, v165
	global_store_short v[0:1], v2, off offset:1760
	s_branch .LBB0_465
